# MLA V^T workspace row pitch 32768 B -> 37120 B (writer and reader), avoids power-of-two row aliasing
# speedup vs baseline: 1.0057x; 1.0057x over previous
; #define MFMA32(a, b, c) __builtin_amdgcn_mfma_f32_32x32x16_bf16((a), (b), (c), 0, 0, 0)
; template <class Epi>
; DI void gemm_tile_s(const bf16_t* __restrict__ A, int lda, const bf16_t* __restrict__ Bt, int ldb, int K, int m0, int n0, char* smem, const Epi& epi) {
;     ...
;   const int r0 = tid >> 3, c0 = tid & 7;
;   const bf16_t* ag = A + (size_t)(m0 + r0) * lda + c0 * 8;
;   const bf16_t* bg = Bt + (size_t)(n0 + r0) * ldb + c0 * 8;
;   const int wofs = r0 * 128 + ((c0 ^ ((r0 >> 1) & 7)) << 4);
;   char* sA = smem; char* sB = smem + 32768;
;   u32x4 ra[4], rb[4];
; #pragma unroll
;   for (int i = 0; i < 4; ++i) { ra[i] = *(const u32x4*)(ag + (size_t)i * 64 * lda); rb[i] = *(const u32x4*)(bg + (size_t)i * 64 * ldb); }
; #pragma unroll
;   for (int i = 0; i < 4; ++i) { *(u32x4*)(sA + wofs + i * 8192) = ra[i]; *(u32x4*)(sB + wofs + i * 8192) = rb[i]; }
;   __syncthreads();
;   const int nk = K >> 6, swz = (lane >> 1) & 7;
;   const int aoff = (64 * wn + lq) * 128, boff = (128 * wm + lq) * 128;
;   for (int kt = 0; kt < nk; ++kt) {
;     const char* cA = sA + (kt & 1) * 65536; const char* cB = sB + (kt & 1) * 65536;
;     const bool more = (kt + 1 < nk);
;     if (more) { ag += 64; bg += 64;
; #pragma unroll
;       for (int i = 0; i < 4; ++i) { ra[i] = *(const u32x4*)(ag + (size_t)i * 64 * lda); rb[i] = *(const u32x4*)(bg + (size_t)i * 64 * ldb); } }
; #pragma unroll
;     for (int s = 0; s < 4; ++s) {
;       const int co = (((2 * s + h) ^ swz) << 4);
;       bf16x8 fa[2], fb[4];
; #pragma unroll
;       for (int ni = 0; ni < 2; ++ni) fa[ni] = *(const bf16x8*)(cB + aoff + ni * 4096 + co);
; #pragma unroll
;       for (int mi = 0; mi < 4; ++mi) fb[mi] = *(const bf16x8*)(cA + boff + mi * 4096 + co);
; #pragma unroll
;       for (int ni = 0; ni < 2; ++ni)
; #pragma unroll
;         for (int mi = 0; mi < 4; ++mi) acc[ni][mi] = MFMA32(fa[ni], fb[mi], acc[ni][mi]);
;     }
.LBB0_282:
	s_or_b64 exec, exec, s[0:1]
	global_load_dwordx2 v[132:133], v1, s[40:41] offset:1224
	v_mov_b32_e32 v144, v206
	s_and_b32 s8, s4, 3
	v_ashrrev_i32_e32 v34, 3, v144
	v_lshlrev_b32_e32 v35, 4, v144
	v_add_u32_e32 v5, s5, v34
	v_and_b32_e32 v0, 0x70, v35
	v_mad_i64_i32 v[2:3], s[0:1], v5, s81, v[2:3]
	v_lshl_add_u64 v[138:139], v[2:3], 0, v[0:1]
	v_add_co_u32_e32 v2, vcc, s85, v138
	s_mov_b32 s0, 0x1239a000
	s_nop 0
	v_addc_co_u32_e32 v3, vcc, 0, v139, vcc
	v_add_co_u32_e32 v134, vcc, s0, v138
	s_waitcnt lgkmcnt(0)
	v_lshl_add_u32 v4, s8, 8, v34
	v_addc_co_u32_e32 v135, vcc, 0, v139, vcc
	s_mov_b32 s0, 0x1244a000
	v_ashrrev_i32_e32 v5, 31, v4
	v_add_co_u32_e32 v136, vcc, s0, v138
	v_lshlrev_b64 v[18:19], 8, v[4:5]
	s_nop 0
	v_addc_co_u32_e32 v137, vcc, 0, v139, vcc
	s_mov_b32 s0, 0x124fa000
	v_add_co_u32_e32 v140, vcc, s0, v138
	s_mov_b32 s0, 0x62a8000
	s_nop 0
	v_addc_co_u32_e32 v141, vcc, 0, v139, vcc
	global_load_dwordx4 v[2:5], v[2:3], off offset:928
	s_nop 0
	global_load_dwordx4 v[6:9], v[134:135], off offset:928
	global_load_dwordx4 v[10:13], v[136:137], off offset:928
	global_load_dwordx4 v[14:17], v[140:141], off offset:928
	v_bfe_u32 v170, v144, 1, 3
	v_lshlrev_b32_e32 v36, 7, v144
	v_xor_b32_e32 v35, v35, v144
	v_lshlrev_b32_e32 v34, 7, v34
	v_and_b32_e32 v185, 0x6f80, v36
	v_ashrrev_i32_e32 v37, 1, v144
	v_and_b32_e32 v184, 31, v144
	v_and_b32_e32 v186, 0xffffff80, v37
	v_bfe_u32 v189, v144, 5, 1
	s_waitcnt vmcnt(0)
	v_lshl_add_u64 v[18:19], v[132:133], 0, v[18:19]
	v_lshl_add_u64 v[142:143], v[18:19], 0, v[0:1]
	v_add_co_u32_e32 v18, vcc, s0, v142
	s_mov_b32 s0, 0x62ac000
	s_nop 0
	v_addc_co_u32_e32 v19, vcc, 0, v143, vcc
	v_add_co_u32_e32 v174, vcc, s0, v142
	s_mov_b32 s0, 0x62b0000
	s_nop 0
	v_addc_co_u32_e32 v175, vcc, 0, v143, vcc
	v_add_co_u32_e32 v178, vcc, s0, v142
	s_mov_b32 s0, 0x62b4000
	s_nop 0
	v_addc_co_u32_e32 v179, vcc, 0, v143, vcc
	v_add_co_u32_e32 v182, vcc, s0, v142
	v_lshrrev_b32_e32 v0, 5, v144
	s_nop 0
	v_addc_co_u32_e32 v183, vcc, 0, v143, vcc
	global_load_dwordx4 v[18:21], v[18:19], off
	s_nop 0
	global_load_dwordx4 v[22:25], v[174:175], off
	global_load_dwordx4 v[26:29], v[178:179], off
	global_load_dwordx4 v[30:33], v[182:183], off
	v_bitop3_b32 v0, v0, v170, 1 bitop3:0x6c
	s_movk_i32 s0, 0x70
	v_lshlrev_b32_e32 v0, 4, v0
	v_and_or_b32 v187, v35, s0, v34
	v_or_b32_e32 v34, v185, v0
	s_mov_b64 s[0:1], 0x122ea3a0
	v_lshl_add_u64 v[138:139], v[138:139], 0, s[0:1]
	s_mov_b64 s[0:1], 0x62a8000
	v_lshl_add_u64 v[142:143], v[142:143], 0, s[0:1]
	v_readfirstlane_b32 s0, v132
	v_readfirstlane_b32 s1, v133
	s_add_u32 s9, s0, 0xeae8000
	s_movk_i32 s0, 0x7f
	s_addc_u32 s10, s1, 0
	s_waitcnt lgkmcnt(0)
	ds_write_b128 v187, v[2:5]
	ds_write_b128 v187, v[6:9] offset:8192
	ds_write_b128 v187, v[10:13] offset:16384
	ds_write_b128 v187, v[14:17] offset:24576
	s_waitcnt vmcnt(0)
	ds_write_b128 v187, v[18:21] offset:32768
	ds_write_b128 v187, v[22:25] offset:40960
	ds_write_b128 v187, v[26:29] offset:49152
	ds_write_b128 v187, v[30:33] offset:57344
	s_waitcnt lgkmcnt(0)
	s_barrier
	ds_read_b128 v[2:5], v34 offset:32768
	v_or_b32_e32 v6, v186, v184
	v_lshlrev_b32_e32 v188, 7, v6
	v_or_b32_e32 v22, v188, v0
	ds_read_b128 v[6:9], v22
	ds_read_b128 v[10:13], v34 offset:36864
	ds_read_b128 v[14:17], v22 offset:4096
	ds_read_b128 v[18:21], v22 offset:8192
	ds_read_b128 v[146:149], v22 offset:12288
	s_waitcnt lgkmcnt(4)
	v_mfma_f32_32x32x16_bf16 v[114:129], v[2:5], v[6:9], 0
	s_waitcnt lgkmcnt(2)
	v_mfma_f32_32x32x16_bf16 v[98:113], v[2:5], v[14:17], 0
	s_waitcnt lgkmcnt(1)
	v_mfma_f32_32x32x16_bf16 v[82:97], v[2:5], v[18:21], 0
	s_waitcnt lgkmcnt(0)
	v_mfma_f32_32x32x16_bf16 v[66:81], v[2:5], v[146:149], 0
	v_bitop3_b32 v2, v189, v170, 2 bitop3:0x36
	v_lshlrev_b32_e32 v190, 4, v2
	v_or_b32_e32 v154, v185, v190
	v_or_b32_e32 v166, v188, v190
	v_mfma_f32_32x32x16_bf16 v[50:65], v[10:13], v[6:9], 0
	v_mfma_f32_32x32x16_bf16 v[34:49], v[10:13], v[14:17], 0
	v_mfma_f32_32x32x16_bf16 v[18:33], v[10:13], v[18:21], 0
	v_mfma_f32_32x32x16_bf16 v[2:17], v[10:13], v[146:149], 0
	ds_read_b128 v[146:149], v154 offset:32768
	ds_read_b128 v[150:153], v166
	ds_read_b128 v[154:157], v154 offset:36864
	ds_read_b128 v[158:161], v166 offset:4096
	ds_read_b128 v[162:165], v166 offset:8192
	ds_read_b128 v[166:169], v166 offset:12288
	s_waitcnt lgkmcnt(4)
	v_mfma_f32_32x32x16_bf16 v[114:129], v[146:149], v[150:153], v[114:129]
	s_waitcnt lgkmcnt(2)
	v_mfma_f32_32x32x16_bf16 v[98:113], v[146:149], v[158:161], v[98:113]
	s_waitcnt lgkmcnt(1)
	v_mfma_f32_32x32x16_bf16 v[82:97], v[146:149], v[162:165], v[82:97]
	s_waitcnt lgkmcnt(0)
	v_mfma_f32_32x32x16_bf16 v[66:81], v[146:149], v[166:169], v[66:81]
	v_bitop3_b32 v146, v189, v170, 4 bitop3:0x36
	v_lshlrev_b32_e32 v191, 4, v146
	v_mfma_f32_32x32x16_bf16 v[34:49], v[154:157], v[158:161], v[34:49]
	v_or_b32_e32 v158, v185, v191
	ds_read_b128 v[146:149], v158 offset:32768
	v_mfma_f32_32x32x16_bf16 v[50:65], v[154:157], v[150:153], v[50:65]
	v_mfma_f32_32x32x16_bf16 v[18:33], v[154:157], v[162:165], v[18:33]
	v_mfma_f32_32x32x16_bf16 v[2:17], v[154:157], v[166:169], v[2:17]
	v_or_b32_e32 v166, v188, v191
	ds_read_b128 v[150:153], v166
	ds_read_b128 v[154:157], v158 offset:36864
	ds_read_b128 v[158:161], v166 offset:4096
	ds_read_b128 v[162:165], v166 offset:8192
	ds_read_b128 v[166:169], v166 offset:12288
	s_waitcnt lgkmcnt(4)
	v_mfma_f32_32x32x16_bf16 v[114:129], v[146:149], v[150:153], v[114:129]
	s_waitcnt lgkmcnt(2)
	v_mfma_f32_32x32x16_bf16 v[98:113], v[146:149], v[158:161], v[98:113]
	s_waitcnt lgkmcnt(1)
	v_mfma_f32_32x32x16_bf16 v[82:97], v[146:149], v[162:165], v[82:97]
	s_waitcnt lgkmcnt(0)
; #define MFMA32(a, b, c) __builtin_amdgcn_mfma_f32_32x32x16_bf16((a), (b), (c), 0, 0, 0)
; template <class Epi>
; DI void gemm_tile_s(const bf16_t* __restrict__ A, int lda, const bf16_t* __restrict__ Bt, int ldb, int K, int m0, int n0, char* smem, const Epi& epi) {
;     ...
;   for (int kt = 0; kt < nk; ++kt) {
;     const char* cA = sA + (kt & 1) * 65536; const char* cB = sB + (kt & 1) * 65536;
;     const bool more = (kt + 1 < nk);
;     if (more) { ag += 64; bg += 64;
; #pragma unroll
;       for (int i = 0; i < 4; ++i) { ra[i] = *(const u32x4*)(ag + (size_t)i * 64 * lda); rb[i] = *(const u32x4*)(bg + (size_t)i * 64 * ldb); } }
; #pragma unroll
;     for (int s = 0; s < 4; ++s) {
;       const int co = (((2 * s + h) ^ swz) << 4);
;       bf16x8 fa[2], fb[4];
; #pragma unroll
;       for (int ni = 0; ni < 2; ++ni) fa[ni] = *(const bf16x8*)(cB + aoff + ni * 4096 + co);
; #pragma unroll
;       for (int mi = 0; mi < 4; ++mi) fb[mi] = *(const bf16x8*)(cA + boff + mi * 4096 + co);
; #pragma unroll
;       for (int ni = 0; ni < 2; ++ni)
; #pragma unroll
;         for (int mi = 0; mi < 4; ++mi) acc[ni][mi] = MFMA32(fa[ni], fb[mi], acc[ni][mi]);
;     }
;     if (more) { char* dA = sA + ((kt + 1) & 1) * 65536; char* dB = sB + ((kt + 1) & 1) * 65536;
; #pragma unroll
;       for (int i = 0; i < 4; ++i) { *(u32x4*)(dA + wofs + i * 8192) = ra[i]; *(u32x4*)(dB + wofs + i * 8192) = rb[i]; } }
;     __syncthreads();
	v_mfma_f32_32x32x16_bf16 v[66:81], v[146:149], v[166:169], v[66:81]
	v_bitop3_b32 v146, v189, v170, 6 bitop3:0x36
	v_lshlrev_b32_e32 v192, 4, v146
	v_mfma_f32_32x32x16_bf16 v[50:65], v[154:157], v[150:153], v[50:65]
	v_mfma_f32_32x32x16_bf16 v[34:49], v[154:157], v[158:161], v[34:49]
	v_mfma_f32_32x32x16_bf16 v[18:33], v[154:157], v[162:165], v[18:33]
	v_mfma_f32_32x32x16_bf16 v[2:17], v[154:157], v[166:169], v[2:17]
	v_or_b32_e32 v154, v185, v192
	ds_read_b128 v[146:149], v154 offset:32768
	v_or_b32_e32 v166, v188, v192
	ds_read_b128 v[150:153], v166
	ds_read_b128 v[154:157], v154 offset:36864
	ds_read_b128 v[158:161], v166 offset:4096
	ds_read_b128 v[162:165], v166 offset:8192
	ds_read_b128 v[166:169], v166 offset:12288
	s_waitcnt lgkmcnt(4)
	v_mfma_f32_32x32x16_bf16 v[114:129], v[146:149], v[150:153], v[114:129]
	s_waitcnt lgkmcnt(2)
	v_mfma_f32_32x32x16_bf16 v[98:113], v[146:149], v[158:161], v[98:113]
	s_waitcnt lgkmcnt(1)
	v_mfma_f32_32x32x16_bf16 v[82:97], v[146:149], v[162:165], v[82:97]
	s_waitcnt lgkmcnt(0)
	v_mfma_f32_32x32x16_bf16 v[66:81], v[146:149], v[166:169], v[66:81]
	v_mfma_f32_32x32x16_bf16 v[50:65], v[154:157], v[150:153], v[50:65]
	global_load_dwordx4 v[146:149], v[138:139], off offset:128
	global_load_dwordx4 v[150:153], v[142:143], off offset:128
	global_load_dwordx4 v[170:173], v[134:135], off offset:1056
	s_nop 0
	global_load_dwordx4 v[174:177], v[174:175], off offset:128
	s_nop 0
	global_load_dwordx4 v[134:137], v[136:137], off offset:1056
	s_nop 0
	global_load_dwordx4 v[178:181], v[178:179], off offset:128
	s_nop 0
	global_load_dwordx4 v[138:141], v[140:141], off offset:1056
	v_add_u32_e32 v142, 0x10000, v187
	v_add_u32_e32 v143, 0x18000, v187
	v_mfma_f32_32x32x16_bf16 v[34:49], v[154:157], v[158:161], v[34:49]
	global_load_dwordx4 v[158:161], v[182:183], off offset:128
	s_waitcnt vmcnt(0) lgkmcnt(0)
	ds_write_b128 v142, v[146:149]
	ds_write_b128 v143, v[150:153]
	ds_write_b128 v142, v[170:173] offset:8192
	ds_write_b128 v143, v[174:177] offset:8192
	ds_write_b128 v142, v[134:137] offset:16384
	ds_write_b128 v143, v[178:181] offset:16384
	ds_write_b128 v142, v[138:141] offset:24576
	ds_write_b128 v143, v[158:161] offset:24576
	v_or_b32_e32 v142, 0x18000, v185
	v_or_b32_e32 v143, v142, v0
	s_waitcnt lgkmcnt(0)
	s_barrier
; #define MFMA32(a, b, c) __builtin_amdgcn_mfma_f32_32x32x16_bf16((a), (b), (c), 0, 0, 0)
; template <class Epi>
; DI void gemm_tile_s(const bf16_t* __restrict__ A, int lda, const bf16_t* __restrict__ Bt, int ldb, int K, int m0, int n0, char* smem, const Epi& epi) {
;     ...
;     for (int s = 0; s < 4; ++s) {
;       const int co = (((2 * s + h) ^ swz) << 4);
;       bf16x8 fa[2], fb[4];
; #pragma unroll
;       for (int ni = 0; ni < 2; ++ni) fa[ni] = *(const bf16x8*)(cB + aoff + ni * 4096 + co);
; #pragma unroll
;       for (int mi = 0; mi < 4; ++mi) fb[mi] = *(const bf16x8*)(cA + boff + mi * 4096 + co);
; #pragma unroll
;       for (int ni = 0; ni < 2; ++ni)
; #pragma unroll
;         for (int mi = 0; mi < 4; ++mi) acc[ni][mi] = MFMA32(fa[ni], fb[mi], acc[ni][mi]);
;     }
;     if (more) { char* dA = sA + ((kt + 1) & 1) * 65536; char* dB = sB + ((kt + 1) & 1) * 65536;
; #pragma unroll
;       for (int i = 0; i < 4; ++i) { *(u32x4*)(dA + wofs + i * 8192) = ra[i]; *(u32x4*)(dB + wofs + i * 8192) = rb[i]; } }
;     __syncthreads();
	ds_read_b128 v[134:137], v143
	v_mfma_f32_32x32x16_bf16 v[18:33], v[154:157], v[162:165], v[18:33]
	v_add_u32_e32 v162, 0x10000, v188
	v_or_b32_e32 v0, v162, v0
	ds_read_b128 v[138:141], v0
	ds_read_b128 v[146:149], v143 offset:4096
	ds_read_b128 v[150:153], v0 offset:4096
	v_or_b32_e32 v143, v162, v190
	v_mfma_f32_32x32x16_bf16 v[2:17], v[154:157], v[166:169], v[2:17]
	ds_read_b128 v[154:157], v0 offset:8192
	ds_read_b128 v[158:161], v0 offset:12288
	v_or_b32_e32 v0, v142, v190
	s_waitcnt lgkmcnt(4)
	v_mfma_f32_32x32x16_bf16 v[114:129], v[134:137], v[138:141], v[114:129]
	s_waitcnt lgkmcnt(2)
	v_mfma_f32_32x32x16_bf16 v[98:113], v[134:137], v[150:153], v[98:113]
	s_waitcnt lgkmcnt(1)
	v_mfma_f32_32x32x16_bf16 v[82:97], v[134:137], v[154:157], v[82:97]
	s_waitcnt lgkmcnt(0)
	v_mfma_f32_32x32x16_bf16 v[66:81], v[134:137], v[158:161], v[66:81]
	ds_read_b128 v[134:137], v0
	v_mfma_f32_32x32x16_bf16 v[50:65], v[146:149], v[138:141], v[50:65]
	v_mfma_f32_32x32x16_bf16 v[34:49], v[146:149], v[150:153], v[34:49]
	v_mfma_f32_32x32x16_bf16 v[18:33], v[146:149], v[154:157], v[18:33]
	v_mfma_f32_32x32x16_bf16 v[2:17], v[146:149], v[158:161], v[2:17]
	ds_read_b128 v[138:141], v143
	ds_read_b128 v[146:149], v0 offset:4096
	ds_read_b128 v[150:153], v143 offset:4096
	ds_read_b128 v[154:157], v143 offset:8192
	ds_read_b128 v[158:161], v143 offset:12288
	v_or_b32_e32 v0, v142, v191
	v_or_b32_e32 v143, v162, v191
	s_waitcnt lgkmcnt(4)
	v_mfma_f32_32x32x16_bf16 v[114:129], v[134:137], v[138:141], v[114:129]
	s_waitcnt lgkmcnt(2)
	v_mfma_f32_32x32x16_bf16 v[98:113], v[134:137], v[150:153], v[98:113]
	s_waitcnt lgkmcnt(1)
	v_mfma_f32_32x32x16_bf16 v[82:97], v[134:137], v[154:157], v[82:97]
	s_waitcnt lgkmcnt(0)
	v_mfma_f32_32x32x16_bf16 v[66:81], v[134:137], v[158:161], v[66:81]
	ds_read_b128 v[134:137], v0
	v_mfma_f32_32x32x16_bf16 v[50:65], v[146:149], v[138:141], v[50:65]
	v_mfma_f32_32x32x16_bf16 v[34:49], v[146:149], v[150:153], v[34:49]
	v_mfma_f32_32x32x16_bf16 v[18:33], v[146:149], v[154:157], v[18:33]
	v_mfma_f32_32x32x16_bf16 v[2:17], v[146:149], v[158:161], v[2:17]
	ds_read_b128 v[138:141], v143
	ds_read_b128 v[146:149], v0 offset:4096
	ds_read_b128 v[150:153], v143 offset:4096
	ds_read_b128 v[154:157], v143 offset:8192
	ds_read_b128 v[158:161], v143 offset:12288
	v_or_b32_e32 v0, v142, v192
	v_or_b32_e32 v142, v162, v192
	s_waitcnt lgkmcnt(4)
	v_mfma_f32_32x32x16_bf16 v[114:129], v[134:137], v[138:141], v[114:129]
	s_waitcnt lgkmcnt(2)
	v_mfma_f32_32x32x16_bf16 v[98:113], v[134:137], v[150:153], v[98:113]
	s_waitcnt lgkmcnt(1)
	v_mfma_f32_32x32x16_bf16 v[82:97], v[134:137], v[154:157], v[82:97]
	s_waitcnt lgkmcnt(0)
	v_mfma_f32_32x32x16_bf16 v[66:81], v[134:137], v[158:161], v[66:81]
	ds_read_b128 v[134:137], v0
	v_mfma_f32_32x32x16_bf16 v[50:65], v[146:149], v[138:141], v[50:65]
	v_mfma_f32_32x32x16_bf16 v[34:49], v[146:149], v[150:153], v[34:49]
	v_mfma_f32_32x32x16_bf16 v[18:33], v[146:149], v[154:157], v[18:33]
	v_mfma_f32_32x32x16_bf16 v[2:17], v[146:149], v[158:161], v[2:17]
	ds_read_b128 v[138:141], v142
	ds_read_b128 v[148:151], v0 offset:4096
	ds_read_b128 v[152:155], v142 offset:4096
	ds_read_b128 v[156:159], v142 offset:8192
	ds_read_b128 v[160:163], v142 offset:12288
	v_and_b32_e32 v0, 0xc0, v144
	s_waitcnt lgkmcnt(0)
	s_barrier
	v_lshl_or_b32 v146, v189, 2, v0
	v_mfma_f32_32x32x16_bf16 v[114:129], v[134:137], v[138:141], v[114:129]
	v_cmp_lt_u32_e64 s[2:3], s0, v0
	v_mfma_f32_32x32x16_bf16 v[98:113], v[134:137], v[152:155], v[98:113]
	v_mfma_f32_32x32x16_bf16 v[82:97], v[134:137], v[156:159], v[82:97]
	v_mfma_f32_32x32x16_bf16 v[66:81], v[134:137], v[160:163], v[66:81]
	v_or_b32_e32 v134, s5, v184
	v_add_u32_e32 v134, v134, v186
	v_subrev_u32_e32 v136, s5, v134
	v_lshl_add_u32 v147, v136, 2, v240
	ds_read_b32 v144, v147
	v_ashrrev_i32_e32 v135, 31, v134
	v_add_u32_e32 v136, 0xffffff80, v146
	v_mfma_f32_32x32x16_bf16 v[50:65], v[148:151], v[138:141], v[50:65]
	v_mfma_f32_32x32x16_bf16 v[34:49], v[148:151], v[152:155], v[34:49]
	v_mfma_f32_32x32x16_bf16 v[18:33], v[148:151], v[156:159], v[18:33]
	v_mfma_f32_32x32x16_bf16 v[2:17], v[148:151], v[160:163], v[2:17]
	s_and_saveexec_b64 s[0:1], s[2:3]
	s_xor_b64 s[0:1], exec, s[0:1]
	s_cbranch_execz .LBB0_284
	s_mul_i32 s11, s8, 0x488000
	v_mov_b32_e32 v137, v1
	s_add_u32 s12, s9, s11
	s_addc_u32 s13, s10, 0
	v_mul_u32_u24_e32 v138, 0x9100, v136
	v_mov_b32_e32 v139, v1
	v_lshl_add_u64 v[138:139], s[12:13], 0, v[138:139]
	s_waitcnt lgkmcnt(0)
	v_mul_f32_e32 v0, v114, v144
	v_lshl_add_u64 v[138:139], v[134:135], 1, v[138:139]
	v_cvt_pk_bf16_f32 v0, v0, s0
	global_store_short v[138:139], v0, off
	v_mul_f32_e32 v0, v115, v144
	v_add_co_u32_e32 v140, vcc, 0x9100, v138
	v_cvt_pk_bf16_f32 v0, v0, s0
	s_nop 0
	v_addc_co_u32_e32 v141, vcc, 0, v139, vcc
	global_store_short v[140:141], v0, off
	v_mul_f32_e32 v0, v116, v144
	v_add_co_u32_e32 v140, vcc, 0x12200, v138
	v_cvt_pk_bf16_f32 v0, v0, s0
	s_nop 0
	v_addc_co_u32_e32 v141, vcc, 0, v139, vcc
	global_store_short v[140:141], v0, off
	v_mul_f32_e32 v0, v117, v144
	v_add_co_u32_e32 v138, vcc, 0x1b300, v138
	v_cvt_pk_bf16_f32 v0, v0, s0
	s_nop 0
	v_addc_co_u32_e32 v139, vcc, 0, v139, vcc
	global_store_short v[138:139], v0, off

.LBB0_286:
	s_or_b64 exec, exec, s[0:1]
	v_add_u32_e32 v140, 0xffffff88, v146
	s_and_saveexec_b64 s[0:1], s[2:3]
	s_xor_b64 s[0:1], exec, s[0:1]
	s_cbranch_execz .LBB0_288
	s_mul_i32 s11, s8, 0x488000
	v_mov_b32_e32 v141, v1
	s_add_u32 s12, s9, s11
	s_addc_u32 s13, s10, 0
	v_mul_u32_u24_e32 v114, 0x9100, v140
	v_mov_b32_e32 v115, v1
	v_lshl_add_u64 v[114:115], s[12:13], 0, v[114:115]
	s_waitcnt lgkmcnt(0)
	v_mul_f32_e32 v116, v118, v144
	v_lshl_add_u64 v[114:115], v[134:135], 1, v[114:115]
	v_cvt_pk_bf16_f32 v116, v116, s0
	global_store_short v[114:115], v116, off
	v_mul_f32_e32 v116, v119, v144
	v_cvt_pk_bf16_f32 v137, v116, s0
	v_add_co_u32_e32 v116, vcc, 0x9100, v114
	s_nop 1
	v_addc_co_u32_e32 v117, vcc, 0, v115, vcc
	global_store_short v[116:117], v137, off
	v_mul_f32_e32 v116, v120, v144
	v_cvt_pk_bf16_f32 v137, v116, s0
	v_add_co_u32_e32 v116, vcc, 0x12200, v114
	s_nop 1
	v_addc_co_u32_e32 v117, vcc, 0, v115, vcc
	global_store_short v[116:117], v137, off
	v_mul_f32_e32 v116, v121, v144
	v_add_co_u32_e32 v114, vcc, 0x1b300, v114
	v_cvt_pk_bf16_f32 v116, v116, s0
	s_nop 0
	v_addc_co_u32_e32 v115, vcc, 0, v115, vcc
	global_store_short v[114:115], v116, off

.LBB0_290:
	s_or_b64 exec, exec, s[0:1]
	v_add_u32_e32 v142, 0xffffff90, v146
	s_and_saveexec_b64 s[0:1], s[2:3]
	s_xor_b64 s[0:1], exec, s[0:1]
	s_cbranch_execz .LBB0_292
	s_mul_i32 s11, s8, 0x488000
	v_mov_b32_e32 v143, v1
	s_add_u32 s12, s9, s11
	s_addc_u32 s13, s10, 0
	v_mul_u32_u24_e32 v114, 0x9100, v142
	v_mov_b32_e32 v115, v1
	v_lshl_add_u64 v[114:115], s[12:13], 0, v[114:115]
	s_waitcnt lgkmcnt(0)
	v_mul_f32_e32 v116, v122, v144
	v_lshl_add_u64 v[114:115], v[134:135], 1, v[114:115]
	v_cvt_pk_bf16_f32 v116, v116, s0
	global_store_short v[114:115], v116, off
	v_mul_f32_e32 v116, v123, v144
	v_cvt_pk_bf16_f32 v118, v116, s0
	v_add_co_u32_e32 v116, vcc, 0x9100, v114
	s_nop 1
	v_addc_co_u32_e32 v117, vcc, 0, v115, vcc
	global_store_short v[116:117], v118, off
	v_mul_f32_e32 v116, v124, v144
	v_cvt_pk_bf16_f32 v118, v116, s0
	v_add_co_u32_e32 v116, vcc, 0x12200, v114
	s_nop 1
	v_addc_co_u32_e32 v117, vcc, 0, v115, vcc
	global_store_short v[116:117], v118, off
	v_mul_f32_e32 v116, v125, v144
	v_add_co_u32_e32 v114, vcc, 0x1b300, v114
	v_cvt_pk_bf16_f32 v116, v116, s0
	s_nop 0
	v_addc_co_u32_e32 v115, vcc, 0, v115, vcc
	global_store_short v[114:115], v116, off

.LBB0_294:
	s_or_b64 exec, exec, s[0:1]
	v_add_u32_e32 v138, 0xffffff98, v146
	s_and_saveexec_b64 s[0:1], s[2:3]
	s_xor_b64 s[0:1], exec, s[0:1]
	s_cbranch_execz .LBB0_296
	s_mul_i32 s11, s8, 0x488000
	v_mov_b32_e32 v139, v1
	s_add_u32 s12, s9, s11
	s_addc_u32 s13, s10, 0
	v_mul_u32_u24_e32 v114, 0x9100, v138
	v_mov_b32_e32 v115, v1
	v_lshl_add_u64 v[114:115], s[12:13], 0, v[114:115]
	s_waitcnt lgkmcnt(0)
	v_mul_f32_e32 v116, v126, v144
	v_lshl_add_u64 v[114:115], v[134:135], 1, v[114:115]
	v_cvt_pk_bf16_f32 v116, v116, s0
	global_store_short v[114:115], v116, off
	v_mul_f32_e32 v116, v127, v144
	v_cvt_pk_bf16_f32 v118, v116, s0
	v_add_co_u32_e32 v116, vcc, 0x9100, v114
	s_nop 1
	v_addc_co_u32_e32 v117, vcc, 0, v115, vcc
	global_store_short v[116:117], v118, off
	v_mul_f32_e32 v116, v128, v144
	v_cvt_pk_bf16_f32 v118, v116, s0
	v_add_co_u32_e32 v116, vcc, 0x12200, v114
	s_nop 1
	v_addc_co_u32_e32 v117, vcc, 0, v115, vcc
	global_store_short v[116:117], v118, off
	v_mul_f32_e32 v116, v129, v144
	v_add_co_u32_e32 v114, vcc, 0x1b300, v114
	v_cvt_pk_bf16_f32 v116, v116, s0
	s_nop 0
	v_addc_co_u32_e32 v115, vcc, 0, v115, vcc
	global_store_short v[114:115], v116, off

.LBB0_325:
	s_or_b64 exec, exec, s[0:1]
	ds_read_b32 v74, v147
	v_add_u32_e32 v68, 0xffffffa0, v146
	s_and_saveexec_b64 s[0:1], s[2:3]
	s_xor_b64 s[0:1], exec, s[0:1]
	s_cbranch_execz .LBB0_327
	s_mul_i32 s11, s8, 0x488000
	v_mov_b32_e32 v69, v1
	s_add_u32 s12, s9, s11
	s_addc_u32 s13, s10, 0
	v_mul_u32_u24_e32 v66, 0x9100, v68
	v_mov_b32_e32 v67, v1
	v_lshl_add_u64 v[66:67], s[12:13], 0, v[66:67]
	s_waitcnt lgkmcnt(0)
	v_mul_f32_e32 v69, v50, v74
	v_lshl_add_u64 v[66:67], v[134:135], 1, v[66:67]
	v_cvt_pk_bf16_f32 v69, v69, s0
	global_store_short v[66:67], v69, off
	v_mul_f32_e32 v69, v51, v74
	v_add_co_u32_e32 v70, vcc, 0x9100, v66
	v_cvt_pk_bf16_f32 v69, v69, s0
	s_nop 0
	v_addc_co_u32_e32 v71, vcc, 0, v67, vcc
	global_store_short v[70:71], v69, off
	v_mul_f32_e32 v69, v52, v74
	v_add_co_u32_e32 v70, vcc, 0x12200, v66
	v_cvt_pk_bf16_f32 v69, v69, s0
	s_nop 0
	v_addc_co_u32_e32 v71, vcc, 0, v67, vcc
	global_store_short v[70:71], v69, off
	v_mul_f32_e32 v69, v53, v74
	v_add_co_u32_e32 v66, vcc, 0x1b300, v66
	v_cvt_pk_bf16_f32 v69, v69, s0
	s_nop 0
	v_addc_co_u32_e32 v67, vcc, 0, v67, vcc
	global_store_short v[66:67], v69, off

.LBB0_329:
	s_or_b64 exec, exec, s[0:1]
	v_add_u32_e32 v72, 0xffffffa8, v146
	s_and_saveexec_b64 s[0:1], s[2:3]
	s_xor_b64 s[0:1], exec, s[0:1]
	s_cbranch_execz .LBB0_331
	s_mul_i32 s11, s8, 0x488000
	v_mov_b32_e32 v73, v1
	s_add_u32 s12, s9, s11
	s_addc_u32 s13, s10, 0
	v_mul_u32_u24_e32 v50, 0x9100, v72
	v_mov_b32_e32 v51, v1
	v_lshl_add_u64 v[50:51], s[12:13], 0, v[50:51]
	s_waitcnt lgkmcnt(0)
	v_mul_f32_e32 v52, v54, v74
	v_lshl_add_u64 v[50:51], v[134:135], 1, v[50:51]
	v_cvt_pk_bf16_f32 v52, v52, s0
	global_store_short v[50:51], v52, off
	v_mul_f32_e32 v52, v55, v74
	v_cvt_pk_bf16_f32 v66, v52, s0
	v_add_co_u32_e32 v52, vcc, 0x9100, v50
	s_nop 1
	v_addc_co_u32_e32 v53, vcc, 0, v51, vcc
	global_store_short v[52:53], v66, off
	v_mul_f32_e32 v52, v56, v74
	v_cvt_pk_bf16_f32 v66, v52, s0
	v_add_co_u32_e32 v52, vcc, 0x12200, v50
	s_nop 1
	v_addc_co_u32_e32 v53, vcc, 0, v51, vcc
	global_store_short v[52:53], v66, off
	v_mul_f32_e32 v52, v57, v74
	v_add_co_u32_e32 v50, vcc, 0x1b300, v50
	v_cvt_pk_bf16_f32 v52, v52, s0
	s_nop 0
	v_addc_co_u32_e32 v51, vcc, 0, v51, vcc
	global_store_short v[50:51], v52, off

.LBB0_333:
	s_or_b64 exec, exec, s[0:1]
	v_add_u32_e32 v70, 0xffffffb0, v146
	s_and_saveexec_b64 s[0:1], s[2:3]
	s_xor_b64 s[0:1], exec, s[0:1]
	s_cbranch_execz .LBB0_335
	s_mul_i32 s11, s8, 0x488000
	v_mov_b32_e32 v71, v1
	s_add_u32 s12, s9, s11
	s_addc_u32 s13, s10, 0
	v_mul_u32_u24_e32 v50, 0x9100, v70
	v_mov_b32_e32 v51, v1
	v_lshl_add_u64 v[50:51], s[12:13], 0, v[50:51]
	s_waitcnt lgkmcnt(0)
	v_mul_f32_e32 v52, v58, v74
	v_lshl_add_u64 v[50:51], v[134:135], 1, v[50:51]
	v_cvt_pk_bf16_f32 v52, v52, s0
	global_store_short v[50:51], v52, off
	v_mul_f32_e32 v52, v59, v74
	v_cvt_pk_bf16_f32 v54, v52, s0
	v_add_co_u32_e32 v52, vcc, 0x9100, v50
	s_nop 1
	v_addc_co_u32_e32 v53, vcc, 0, v51, vcc
	global_store_short v[52:53], v54, off
	v_mul_f32_e32 v52, v60, v74
	v_cvt_pk_bf16_f32 v54, v52, s0
	v_add_co_u32_e32 v52, vcc, 0x12200, v50
	s_nop 1
	v_addc_co_u32_e32 v53, vcc, 0, v51, vcc
	global_store_short v[52:53], v54, off
	v_mul_f32_e32 v52, v61, v74
	v_add_co_u32_e32 v50, vcc, 0x1b300, v50
	v_cvt_pk_bf16_f32 v52, v52, s0
	s_nop 0
	v_addc_co_u32_e32 v51, vcc, 0, v51, vcc
	global_store_short v[50:51], v52, off

.LBB0_337:
	s_or_b64 exec, exec, s[0:1]
	v_add_u32_e32 v66, 0xffffffb8, v146
	s_and_saveexec_b64 s[0:1], s[2:3]
	s_xor_b64 s[0:1], exec, s[0:1]
	s_cbranch_execz .LBB0_339
	s_mul_i32 s11, s8, 0x488000
	v_mov_b32_e32 v67, v1
	s_add_u32 s12, s9, s11
	s_addc_u32 s13, s10, 0
	v_mul_u32_u24_e32 v50, 0x9100, v66
	v_mov_b32_e32 v51, v1
	v_lshl_add_u64 v[50:51], s[12:13], 0, v[50:51]
	s_waitcnt lgkmcnt(0)
	v_mul_f32_e32 v52, v62, v74
	v_lshl_add_u64 v[50:51], v[134:135], 1, v[50:51]
	v_cvt_pk_bf16_f32 v52, v52, s0
	global_store_short v[50:51], v52, off
	v_mul_f32_e32 v52, v63, v74
	v_cvt_pk_bf16_f32 v54, v52, s0
	v_add_co_u32_e32 v52, vcc, 0x9100, v50
	s_nop 1
	v_addc_co_u32_e32 v53, vcc, 0, v51, vcc
	global_store_short v[52:53], v54, off
	v_mul_f32_e32 v52, v64, v74
	v_cvt_pk_bf16_f32 v54, v52, s0
	v_add_co_u32_e32 v52, vcc, 0x12200, v50
	s_nop 1
	v_addc_co_u32_e32 v53, vcc, 0, v51, vcc
	global_store_short v[52:53], v54, off
	v_mul_f32_e32 v52, v65, v74
	v_add_co_u32_e32 v50, vcc, 0x1b300, v50
	v_cvt_pk_bf16_f32 v52, v52, s0
	s_nop 0
	v_addc_co_u32_e32 v51, vcc, 0, v51, vcc
	global_store_short v[50:51], v52, off

.LBB0_368:
	s_mul_i32 s11, s8, 0x488000
	v_mov_b32_e32 v137, v1
	s_add_u32 s12, s9, s11
	s_addc_u32 s13, s10, 0
	v_mul_u32_u24_e32 v118, 0x9100, v136
	v_mov_b32_e32 v119, v1
	v_lshl_add_u64 v[118:119], s[12:13], 0, v[118:119]
	s_waitcnt lgkmcnt(0)
	v_mul_f32_e32 v120, v98, v116
	v_lshl_add_u64 v[118:119], v[114:115], 1, v[118:119]
	v_cvt_pk_bf16_f32 v120, v120, s0
	global_store_short v[118:119], v120, off
	v_mul_f32_e32 v120, v99, v116
	v_cvt_pk_bf16_f32 v122, v120, s0
	v_add_co_u32_e32 v120, vcc, 0x9100, v118
	s_nop 1
	v_addc_co_u32_e32 v121, vcc, 0, v119, vcc
	global_store_short v[120:121], v122, off
	v_mul_f32_e32 v120, v100, v116
	v_cvt_pk_bf16_f32 v122, v120, s0
	v_add_co_u32_e32 v120, vcc, 0x12200, v118
	s_nop 1
	v_addc_co_u32_e32 v121, vcc, 0, v119, vcc
	global_store_short v[120:121], v122, off
	v_mul_f32_e32 v120, v101, v116
	v_add_co_u32_e32 v118, vcc, 0x1b300, v118
	v_cvt_pk_bf16_f32 v120, v120, s0
	s_nop 0
	v_addc_co_u32_e32 v119, vcc, 0, v119, vcc
	global_store_short v[118:119], v120, off
	s_andn2_saveexec_b64 s[0:1], s[0:1]
	s_cbranch_execz .LBB0_300

.LBB0_370:
	s_mul_i32 s11, s8, 0x488000
	v_mov_b32_e32 v141, v1
	s_add_u32 s12, s9, s11
	s_addc_u32 s13, s10, 0
	v_mul_u32_u24_e32 v98, 0x9100, v140
	v_mov_b32_e32 v99, v1
	v_lshl_add_u64 v[98:99], s[12:13], 0, v[98:99]
	s_waitcnt lgkmcnt(0)
	v_mul_f32_e32 v100, v102, v116
	v_lshl_add_u64 v[98:99], v[114:115], 1, v[98:99]
	v_cvt_pk_bf16_f32 v100, v100, s0
	global_store_short v[98:99], v100, off
	v_mul_f32_e32 v100, v103, v116
	v_cvt_pk_bf16_f32 v118, v100, s0
	v_add_co_u32_e32 v100, vcc, 0x9100, v98
	s_nop 1
	v_addc_co_u32_e32 v101, vcc, 0, v99, vcc
	global_store_short v[100:101], v118, off
	v_mul_f32_e32 v100, v104, v116
	v_cvt_pk_bf16_f32 v118, v100, s0
	v_add_co_u32_e32 v100, vcc, 0x12200, v98
	s_nop 1
	v_addc_co_u32_e32 v101, vcc, 0, v99, vcc
	global_store_short v[100:101], v118, off
	v_mul_f32_e32 v100, v105, v116
	v_add_co_u32_e32 v98, vcc, 0x1b300, v98
	v_cvt_pk_bf16_f32 v100, v100, s0
	s_nop 0
	v_addc_co_u32_e32 v99, vcc, 0, v99, vcc
	global_store_short v[98:99], v100, off
	s_andn2_saveexec_b64 s[0:1], s[0:1]
	s_cbranch_execz .LBB0_302

.LBB0_372:
	s_mul_i32 s11, s8, 0x488000
	v_mov_b32_e32 v143, v1
	s_add_u32 s12, s9, s11
	s_addc_u32 s13, s10, 0
	v_mul_u32_u24_e32 v98, 0x9100, v142
	v_mov_b32_e32 v99, v1
	v_lshl_add_u64 v[98:99], s[12:13], 0, v[98:99]
	s_waitcnt lgkmcnt(0)
	v_mul_f32_e32 v100, v106, v116
	v_lshl_add_u64 v[98:99], v[114:115], 1, v[98:99]
	v_cvt_pk_bf16_f32 v100, v100, s0
	global_store_short v[98:99], v100, off
	v_mul_f32_e32 v100, v107, v116
	v_cvt_pk_bf16_f32 v102, v100, s0
	v_add_co_u32_e32 v100, vcc, 0x9100, v98
	s_nop 1
	v_addc_co_u32_e32 v101, vcc, 0, v99, vcc
	global_store_short v[100:101], v102, off
	v_mul_f32_e32 v100, v108, v116
	v_cvt_pk_bf16_f32 v102, v100, s0
	v_add_co_u32_e32 v100, vcc, 0x12200, v98
	s_nop 1
	v_addc_co_u32_e32 v101, vcc, 0, v99, vcc
	global_store_short v[100:101], v102, off
	v_mul_f32_e32 v100, v109, v116
	v_add_co_u32_e32 v98, vcc, 0x1b300, v98
	v_cvt_pk_bf16_f32 v100, v100, s0
	s_nop 0
	v_addc_co_u32_e32 v99, vcc, 0, v99, vcc
	global_store_short v[98:99], v100, off
	s_andn2_saveexec_b64 s[0:1], s[0:1]
	s_cbranch_execz .LBB0_304

.LBB0_374:
	s_mul_i32 s11, s8, 0x488000
	v_mov_b32_e32 v139, v1
	s_add_u32 s12, s9, s11
	s_addc_u32 s13, s10, 0
	v_mul_u32_u24_e32 v98, 0x9100, v138
	v_mov_b32_e32 v99, v1
	v_lshl_add_u64 v[98:99], s[12:13], 0, v[98:99]
	s_waitcnt lgkmcnt(0)
	v_mul_f32_e32 v100, v110, v116
	v_lshl_add_u64 v[98:99], v[114:115], 1, v[98:99]
	v_cvt_pk_bf16_f32 v100, v100, s0
	global_store_short v[98:99], v100, off
	v_mul_f32_e32 v100, v111, v116
	v_cvt_pk_bf16_f32 v102, v100, s0
	v_add_co_u32_e32 v100, vcc, 0x9100, v98
	s_nop 1
	v_addc_co_u32_e32 v101, vcc, 0, v99, vcc
	global_store_short v[100:101], v102, off
	v_mul_f32_e32 v100, v112, v116
	v_cvt_pk_bf16_f32 v102, v100, s0
	v_add_co_u32_e32 v100, vcc, 0x12200, v98
	s_nop 1
	v_addc_co_u32_e32 v101, vcc, 0, v99, vcc
	global_store_short v[100:101], v102, off
	v_mul_f32_e32 v100, v113, v116
	v_add_co_u32_e32 v98, vcc, 0x1b300, v98
	v_cvt_pk_bf16_f32 v100, v100, s0
	s_nop 0
	v_addc_co_u32_e32 v99, vcc, 0, v99, vcc
	global_store_short v[98:99], v100, off
	s_andn2_saveexec_b64 s[0:1], s[0:1]
	s_cbranch_execnz .LBB0_306
	s_branch .LBB0_307
.LBB0_375:
	s_mul_i32 s11, s8, 0x488000
	v_mov_b32_e32 v137, v1
	s_add_u32 s12, s9, s11
	s_addc_u32 s13, s10, 0
	v_mul_u32_u24_e32 v102, 0x9100, v136
	v_mov_b32_e32 v103, v1
	v_lshl_add_u64 v[102:103], s[12:13], 0, v[102:103]
	s_waitcnt lgkmcnt(0)
	v_mul_f32_e32 v104, v82, v100
	v_lshl_add_u64 v[102:103], v[98:99], 1, v[102:103]
	v_cvt_pk_bf16_f32 v104, v104, s0
	global_store_short v[102:103], v104, off
	v_mul_f32_e32 v104, v83, v100
	v_cvt_pk_bf16_f32 v106, v104, s0
	v_add_co_u32_e32 v104, vcc, 0x9100, v102
	s_nop 1
	v_addc_co_u32_e32 v105, vcc, 0, v103, vcc
	global_store_short v[104:105], v106, off
	v_mul_f32_e32 v104, v84, v100
	v_cvt_pk_bf16_f32 v106, v104, s0
	v_add_co_u32_e32 v104, vcc, 0x12200, v102
	s_nop 1
	v_addc_co_u32_e32 v105, vcc, 0, v103, vcc
	global_store_short v[104:105], v106, off
	v_mul_f32_e32 v104, v85, v100
	v_add_co_u32_e32 v102, vcc, 0x1b300, v102
	v_cvt_pk_bf16_f32 v104, v104, s0
	s_nop 0
	v_addc_co_u32_e32 v103, vcc, 0, v103, vcc
	global_store_short v[102:103], v104, off
	s_andn2_saveexec_b64 s[0:1], s[0:1]
	s_cbranch_execz .LBB0_309

.LBB0_377:
	s_mul_i32 s11, s8, 0x488000
	v_mov_b32_e32 v141, v1
	s_add_u32 s12, s9, s11
	s_addc_u32 s13, s10, 0
	v_mul_u32_u24_e32 v82, 0x9100, v140
	v_mov_b32_e32 v83, v1
	v_lshl_add_u64 v[82:83], s[12:13], 0, v[82:83]
	s_waitcnt lgkmcnt(0)
	v_mul_f32_e32 v84, v86, v100
	v_lshl_add_u64 v[82:83], v[98:99], 1, v[82:83]
	v_cvt_pk_bf16_f32 v84, v84, s0
	global_store_short v[82:83], v84, off
	v_mul_f32_e32 v84, v87, v100
	v_cvt_pk_bf16_f32 v102, v84, s0
	v_add_co_u32_e32 v84, vcc, 0x9100, v82
	s_nop 1
	v_addc_co_u32_e32 v85, vcc, 0, v83, vcc
	global_store_short v[84:85], v102, off
	v_mul_f32_e32 v84, v88, v100
	v_cvt_pk_bf16_f32 v102, v84, s0
	v_add_co_u32_e32 v84, vcc, 0x12200, v82
	s_nop 1
	v_addc_co_u32_e32 v85, vcc, 0, v83, vcc
	global_store_short v[84:85], v102, off
	v_mul_f32_e32 v84, v89, v100
	v_add_co_u32_e32 v82, vcc, 0x1b300, v82
	v_cvt_pk_bf16_f32 v84, v84, s0
	s_nop 0
	v_addc_co_u32_e32 v83, vcc, 0, v83, vcc
	global_store_short v[82:83], v84, off
	s_andn2_saveexec_b64 s[0:1], s[0:1]
	s_cbranch_execz .LBB0_311

.LBB0_379:
	s_mul_i32 s11, s8, 0x488000
	v_mov_b32_e32 v143, v1
	s_add_u32 s12, s9, s11
	s_addc_u32 s13, s10, 0
	v_mul_u32_u24_e32 v82, 0x9100, v142
	v_mov_b32_e32 v83, v1
	v_lshl_add_u64 v[82:83], s[12:13], 0, v[82:83]
	s_waitcnt lgkmcnt(0)
	v_mul_f32_e32 v84, v90, v100
	v_lshl_add_u64 v[82:83], v[98:99], 1, v[82:83]
	v_cvt_pk_bf16_f32 v84, v84, s0
	global_store_short v[82:83], v84, off
	v_mul_f32_e32 v84, v91, v100
	v_cvt_pk_bf16_f32 v86, v84, s0
	v_add_co_u32_e32 v84, vcc, 0x9100, v82
	s_nop 1
	v_addc_co_u32_e32 v85, vcc, 0, v83, vcc
	global_store_short v[84:85], v86, off
	v_mul_f32_e32 v84, v92, v100
	v_cvt_pk_bf16_f32 v86, v84, s0
	v_add_co_u32_e32 v84, vcc, 0x12200, v82
	s_nop 1
	v_addc_co_u32_e32 v85, vcc, 0, v83, vcc
	global_store_short v[84:85], v86, off
	v_mul_f32_e32 v84, v93, v100
	v_add_co_u32_e32 v82, vcc, 0x1b300, v82
	v_cvt_pk_bf16_f32 v84, v84, s0
	s_nop 0
	v_addc_co_u32_e32 v83, vcc, 0, v83, vcc
	global_store_short v[82:83], v84, off
	s_andn2_saveexec_b64 s[0:1], s[0:1]
	s_cbranch_execz .LBB0_313

.LBB0_381:
	s_mul_i32 s11, s8, 0x488000
	v_mov_b32_e32 v139, v1
	s_add_u32 s12, s9, s11
	s_addc_u32 s13, s10, 0
	v_mul_u32_u24_e32 v82, 0x9100, v138
	v_mov_b32_e32 v83, v1
	v_lshl_add_u64 v[82:83], s[12:13], 0, v[82:83]
	s_waitcnt lgkmcnt(0)
	v_mul_f32_e32 v84, v94, v100
	v_lshl_add_u64 v[82:83], v[98:99], 1, v[82:83]
	v_cvt_pk_bf16_f32 v84, v84, s0
	global_store_short v[82:83], v84, off
	v_mul_f32_e32 v84, v95, v100
	v_cvt_pk_bf16_f32 v86, v84, s0
	v_add_co_u32_e32 v84, vcc, 0x9100, v82
	s_nop 1
	v_addc_co_u32_e32 v85, vcc, 0, v83, vcc
	global_store_short v[84:85], v86, off
	v_mul_f32_e32 v84, v96, v100
	v_cvt_pk_bf16_f32 v86, v84, s0
	v_add_co_u32_e32 v84, vcc, 0x12200, v82
	s_nop 1
	v_addc_co_u32_e32 v85, vcc, 0, v83, vcc
	global_store_short v[84:85], v86, off
	v_mul_f32_e32 v84, v97, v100
	v_add_co_u32_e32 v82, vcc, 0x1b300, v82
	v_cvt_pk_bf16_f32 v84, v84, s0
	s_nop 0
	v_addc_co_u32_e32 v83, vcc, 0, v83, vcc
	global_store_short v[82:83], v84, off
	s_andn2_saveexec_b64 s[0:1], s[0:1]
	s_cbranch_execnz .LBB0_315
	s_branch .LBB0_316
.LBB0_382:
	s_mul_i32 s11, s8, 0x488000
	v_mov_b32_e32 v137, v1
	s_add_u32 s12, s9, s11
	s_addc_u32 s13, s10, 0
	v_mul_u32_u24_e32 v86, 0x9100, v136
	v_mov_b32_e32 v87, v1
	v_lshl_add_u64 v[86:87], s[12:13], 0, v[86:87]
	s_waitcnt lgkmcnt(0)
	v_mul_f32_e32 v88, v66, v84
	v_lshl_add_u64 v[86:87], v[82:83], 1, v[86:87]
	v_cvt_pk_bf16_f32 v88, v88, s0
	global_store_short v[86:87], v88, off
	v_mul_f32_e32 v88, v67, v84
	v_cvt_pk_bf16_f32 v90, v88, s0
	v_add_co_u32_e32 v88, vcc, 0x9100, v86
	s_nop 1
	v_addc_co_u32_e32 v89, vcc, 0, v87, vcc
	global_store_short v[88:89], v90, off
	v_mul_f32_e32 v88, v68, v84
	v_cvt_pk_bf16_f32 v90, v88, s0
	v_add_co_u32_e32 v88, vcc, 0x12200, v86
	s_nop 1
	v_addc_co_u32_e32 v89, vcc, 0, v87, vcc
	global_store_short v[88:89], v90, off
	v_mul_f32_e32 v88, v69, v84
	v_add_co_u32_e32 v86, vcc, 0x1b300, v86
	v_cvt_pk_bf16_f32 v88, v88, s0
	s_nop 0
	v_addc_co_u32_e32 v87, vcc, 0, v87, vcc
	global_store_short v[86:87], v88, off
	s_andn2_saveexec_b64 s[0:1], s[0:1]
	s_cbranch_execz .LBB0_318

.LBB0_384:
	s_mul_i32 s11, s8, 0x488000
	v_mov_b32_e32 v141, v1
	s_add_u32 s12, s9, s11
	s_addc_u32 s13, s10, 0
	v_mul_u32_u24_e32 v66, 0x9100, v140
	v_mov_b32_e32 v67, v1
	v_lshl_add_u64 v[66:67], s[12:13], 0, v[66:67]
	s_waitcnt lgkmcnt(0)
	v_mul_f32_e32 v68, v70, v84
	v_lshl_add_u64 v[66:67], v[82:83], 1, v[66:67]
	v_cvt_pk_bf16_f32 v68, v68, s0
	global_store_short v[66:67], v68, off
	v_mul_f32_e32 v68, v71, v84
	v_cvt_pk_bf16_f32 v86, v68, s0
	v_add_co_u32_e32 v68, vcc, 0x9100, v66
	s_nop 1
	v_addc_co_u32_e32 v69, vcc, 0, v67, vcc
	global_store_short v[68:69], v86, off
	v_mul_f32_e32 v68, v72, v84
	v_cvt_pk_bf16_f32 v86, v68, s0
	v_add_co_u32_e32 v68, vcc, 0x12200, v66
	s_nop 1
	v_addc_co_u32_e32 v69, vcc, 0, v67, vcc
	global_store_short v[68:69], v86, off
	v_mul_f32_e32 v68, v73, v84
	v_add_co_u32_e32 v66, vcc, 0x1b300, v66
	v_cvt_pk_bf16_f32 v68, v68, s0
	s_nop 0
	v_addc_co_u32_e32 v67, vcc, 0, v67, vcc
	global_store_short v[66:67], v68, off
	s_andn2_saveexec_b64 s[0:1], s[0:1]
	s_cbranch_execz .LBB0_320

.LBB0_386:
	s_mul_i32 s11, s8, 0x488000
	v_mov_b32_e32 v143, v1
	s_add_u32 s12, s9, s11
	s_addc_u32 s13, s10, 0
	v_mul_u32_u24_e32 v66, 0x9100, v142
	v_mov_b32_e32 v67, v1
	v_lshl_add_u64 v[66:67], s[12:13], 0, v[66:67]
	s_waitcnt lgkmcnt(0)
	v_mul_f32_e32 v68, v74, v84
	v_lshl_add_u64 v[66:67], v[82:83], 1, v[66:67]
	v_cvt_pk_bf16_f32 v68, v68, s0
	global_store_short v[66:67], v68, off
	v_mul_f32_e32 v68, v75, v84
	v_cvt_pk_bf16_f32 v70, v68, s0
	v_add_co_u32_e32 v68, vcc, 0x9100, v66
	s_nop 1
	v_addc_co_u32_e32 v69, vcc, 0, v67, vcc
	global_store_short v[68:69], v70, off
	v_mul_f32_e32 v68, v76, v84
	v_cvt_pk_bf16_f32 v70, v68, s0
	v_add_co_u32_e32 v68, vcc, 0x12200, v66
	s_nop 1
	v_addc_co_u32_e32 v69, vcc, 0, v67, vcc
	global_store_short v[68:69], v70, off
	v_mul_f32_e32 v68, v77, v84
	v_add_co_u32_e32 v66, vcc, 0x1b300, v66
	v_cvt_pk_bf16_f32 v68, v68, s0
	s_nop 0
	v_addc_co_u32_e32 v67, vcc, 0, v67, vcc
	global_store_short v[66:67], v68, off
	s_andn2_saveexec_b64 s[0:1], s[0:1]
	s_cbranch_execz .LBB0_322

.LBB0_388:
	s_mul_i32 s11, s8, 0x488000
	v_mov_b32_e32 v139, v1
	s_add_u32 s12, s9, s11
	s_addc_u32 s13, s10, 0
	v_mul_u32_u24_e32 v66, 0x9100, v138
	v_mov_b32_e32 v67, v1
	v_lshl_add_u64 v[66:67], s[12:13], 0, v[66:67]
	s_waitcnt lgkmcnt(0)
	v_mul_f32_e32 v68, v78, v84
	v_lshl_add_u64 v[66:67], v[82:83], 1, v[66:67]
	v_cvt_pk_bf16_f32 v68, v68, s0
	global_store_short v[66:67], v68, off
	v_mul_f32_e32 v68, v79, v84
	v_cvt_pk_bf16_f32 v70, v68, s0
	v_add_co_u32_e32 v68, vcc, 0x9100, v66
	s_nop 1
	v_addc_co_u32_e32 v69, vcc, 0, v67, vcc
	global_store_short v[68:69], v70, off
	v_mul_f32_e32 v68, v80, v84
	v_cvt_pk_bf16_f32 v70, v68, s0
	v_add_co_u32_e32 v68, vcc, 0x12200, v66
	s_nop 1
	v_addc_co_u32_e32 v69, vcc, 0, v67, vcc
	global_store_short v[68:69], v70, off
	v_mul_f32_e32 v68, v81, v84
	v_add_co_u32_e32 v66, vcc, 0x1b300, v66
	v_cvt_pk_bf16_f32 v68, v68, s0
	s_nop 0
	v_addc_co_u32_e32 v67, vcc, 0, v67, vcc
	global_store_short v[66:67], v68, off
	s_andn2_saveexec_b64 s[0:1], s[0:1]
	s_cbranch_execnz .LBB0_324
	s_branch .LBB0_325
.LBB0_389:
	s_mul_i32 s11, s8, 0x488000
	v_mov_b32_e32 v69, v1
	s_add_u32 s12, s9, s11
	s_addc_u32 s13, s10, 0
	v_mul_u32_u24_e32 v52, 0x9100, v68
	v_mov_b32_e32 v53, v1
	v_lshl_add_u64 v[52:53], s[12:13], 0, v[52:53]
	s_waitcnt lgkmcnt(0)
	v_mul_f32_e32 v51, v34, v50
	v_lshl_add_u64 v[52:53], v[114:115], 1, v[52:53]
	v_cvt_pk_bf16_f32 v51, v51, s0
	global_store_short v[52:53], v51, off
	v_mul_f32_e32 v51, v35, v50
	v_add_co_u32_e32 v54, vcc, 0x9100, v52
	v_cvt_pk_bf16_f32 v51, v51, s0
	s_nop 0
	v_addc_co_u32_e32 v55, vcc, 0, v53, vcc
	global_store_short v[54:55], v51, off
	v_mul_f32_e32 v51, v36, v50
	v_add_co_u32_e32 v54, vcc, 0x12200, v52
	v_cvt_pk_bf16_f32 v51, v51, s0
	s_nop 0
	v_addc_co_u32_e32 v55, vcc, 0, v53, vcc
	global_store_short v[54:55], v51, off
	v_mul_f32_e32 v51, v37, v50
	v_add_co_u32_e32 v52, vcc, 0x1b300, v52
	v_cvt_pk_bf16_f32 v51, v51, s0
	s_nop 0
	v_addc_co_u32_e32 v53, vcc, 0, v53, vcc
	global_store_short v[52:53], v51, off
	s_andn2_saveexec_b64 s[0:1], s[0:1]
	s_cbranch_execz .LBB0_343

.LBB0_391:
	s_mul_i32 s11, s8, 0x488000
	v_mov_b32_e32 v73, v1
	s_add_u32 s12, s9, s11
	s_addc_u32 s13, s10, 0
	v_mul_u32_u24_e32 v34, 0x9100, v72
	v_mov_b32_e32 v35, v1
	v_lshl_add_u64 v[34:35], s[12:13], 0, v[34:35]
	s_waitcnt lgkmcnt(0)
	v_mul_f32_e32 v36, v38, v50
	v_lshl_add_u64 v[34:35], v[114:115], 1, v[34:35]
	v_cvt_pk_bf16_f32 v36, v36, s0
	global_store_short v[34:35], v36, off
	v_mul_f32_e32 v36, v39, v50
	v_cvt_pk_bf16_f32 v51, v36, s0
	v_add_co_u32_e32 v36, vcc, 0x9100, v34
	s_nop 1
	v_addc_co_u32_e32 v37, vcc, 0, v35, vcc
	global_store_short v[36:37], v51, off
	v_mul_f32_e32 v36, v40, v50
	v_cvt_pk_bf16_f32 v51, v36, s0
	v_add_co_u32_e32 v36, vcc, 0x12200, v34
	s_nop 1
	v_addc_co_u32_e32 v37, vcc, 0, v35, vcc
	global_store_short v[36:37], v51, off
	v_mul_f32_e32 v36, v41, v50
	v_add_co_u32_e32 v34, vcc, 0x1b300, v34
	v_cvt_pk_bf16_f32 v36, v36, s0
	s_nop 0
	v_addc_co_u32_e32 v35, vcc, 0, v35, vcc
	global_store_short v[34:35], v36, off
	s_andn2_saveexec_b64 s[0:1], s[0:1]
	s_cbranch_execz .LBB0_345

.LBB0_393:
	s_mul_i32 s11, s8, 0x488000
	v_mov_b32_e32 v71, v1
	s_add_u32 s12, s9, s11
	s_addc_u32 s13, s10, 0
	v_mul_u32_u24_e32 v34, 0x9100, v70
	v_mov_b32_e32 v35, v1
	v_lshl_add_u64 v[34:35], s[12:13], 0, v[34:35]
	s_waitcnt lgkmcnt(0)
	v_mul_f32_e32 v36, v42, v50
	v_lshl_add_u64 v[34:35], v[114:115], 1, v[34:35]
	v_cvt_pk_bf16_f32 v36, v36, s0
	global_store_short v[34:35], v36, off
	v_mul_f32_e32 v36, v43, v50
	v_cvt_pk_bf16_f32 v38, v36, s0
	v_add_co_u32_e32 v36, vcc, 0x9100, v34
	s_nop 1
	v_addc_co_u32_e32 v37, vcc, 0, v35, vcc
	global_store_short v[36:37], v38, off
	v_mul_f32_e32 v36, v44, v50
	v_cvt_pk_bf16_f32 v38, v36, s0
	v_add_co_u32_e32 v36, vcc, 0x12200, v34
	s_nop 1
	v_addc_co_u32_e32 v37, vcc, 0, v35, vcc
	global_store_short v[36:37], v38, off
	v_mul_f32_e32 v36, v45, v50
	v_add_co_u32_e32 v34, vcc, 0x1b300, v34
	v_cvt_pk_bf16_f32 v36, v36, s0
	s_nop 0
	v_addc_co_u32_e32 v35, vcc, 0, v35, vcc
	global_store_short v[34:35], v36, off
	s_andn2_saveexec_b64 s[0:1], s[0:1]
	s_cbranch_execz .LBB0_347

.LBB0_395:
	s_mul_i32 s11, s8, 0x488000
	v_mov_b32_e32 v67, v1
	s_add_u32 s12, s9, s11
	s_addc_u32 s13, s10, 0
	v_mul_u32_u24_e32 v34, 0x9100, v66
	v_mov_b32_e32 v35, v1
	v_lshl_add_u64 v[34:35], s[12:13], 0, v[34:35]
	s_waitcnt lgkmcnt(0)
	v_mul_f32_e32 v36, v46, v50
	v_lshl_add_u64 v[34:35], v[114:115], 1, v[34:35]
	v_cvt_pk_bf16_f32 v36, v36, s0
	global_store_short v[34:35], v36, off
	v_mul_f32_e32 v36, v47, v50
	v_cvt_pk_bf16_f32 v38, v36, s0
	v_add_co_u32_e32 v36, vcc, 0x9100, v34
	s_nop 1
	v_addc_co_u32_e32 v37, vcc, 0, v35, vcc
	global_store_short v[36:37], v38, off
	v_mul_f32_e32 v36, v48, v50
	v_cvt_pk_bf16_f32 v38, v36, s0
	v_add_co_u32_e32 v36, vcc, 0x12200, v34
	s_nop 1
	v_addc_co_u32_e32 v37, vcc, 0, v35, vcc
	global_store_short v[36:37], v38, off
	v_mul_f32_e32 v36, v49, v50
	v_add_co_u32_e32 v34, vcc, 0x1b300, v34
	v_cvt_pk_bf16_f32 v36, v36, s0
	s_nop 0
	v_addc_co_u32_e32 v35, vcc, 0, v35, vcc
	global_store_short v[34:35], v36, off
	s_andn2_saveexec_b64 s[0:1], s[0:1]
	s_cbranch_execnz .LBB0_349
	s_branch .LBB0_350
.LBB0_396:
	s_mul_i32 s11, s8, 0x488000
	v_mov_b32_e32 v69, v1
	s_add_u32 s12, s9, s11
	s_addc_u32 s13, s10, 0
	v_mul_u32_u24_e32 v36, 0x9100, v68
	v_mov_b32_e32 v37, v1
	v_lshl_add_u64 v[36:37], s[12:13], 0, v[36:37]
	s_waitcnt lgkmcnt(0)
	v_mul_f32_e32 v35, v18, v34
	v_lshl_add_u64 v[36:37], v[98:99], 1, v[36:37]
	v_cvt_pk_bf16_f32 v35, v35, s0
	global_store_short v[36:37], v35, off
	v_mul_f32_e32 v35, v19, v34
	v_add_co_u32_e32 v38, vcc, 0x9100, v36
	v_cvt_pk_bf16_f32 v35, v35, s0
	s_nop 0
	v_addc_co_u32_e32 v39, vcc, 0, v37, vcc
	global_store_short v[38:39], v35, off
	v_mul_f32_e32 v35, v20, v34
	v_add_co_u32_e32 v38, vcc, 0x12200, v36
	v_cvt_pk_bf16_f32 v35, v35, s0
	s_nop 0
	v_addc_co_u32_e32 v39, vcc, 0, v37, vcc
	global_store_short v[38:39], v35, off
	v_mul_f32_e32 v35, v21, v34
	v_add_co_u32_e32 v36, vcc, 0x1b300, v36
	v_cvt_pk_bf16_f32 v35, v35, s0
	s_nop 0
	v_addc_co_u32_e32 v37, vcc, 0, v37, vcc
	global_store_short v[36:37], v35, off
	s_andn2_saveexec_b64 s[0:1], s[0:1]
	s_cbranch_execz .LBB0_352

.LBB0_398:
	s_mul_i32 s11, s8, 0x488000
	v_mov_b32_e32 v73, v1
	s_add_u32 s12, s9, s11
	s_addc_u32 s13, s10, 0
	v_mul_u32_u24_e32 v18, 0x9100, v72
	v_mov_b32_e32 v19, v1
	v_lshl_add_u64 v[18:19], s[12:13], 0, v[18:19]
	s_waitcnt lgkmcnt(0)
	v_mul_f32_e32 v20, v22, v34
	v_lshl_add_u64 v[18:19], v[98:99], 1, v[18:19]
	v_cvt_pk_bf16_f32 v20, v20, s0
	global_store_short v[18:19], v20, off
	v_mul_f32_e32 v20, v23, v34
	v_cvt_pk_bf16_f32 v35, v20, s0
	v_add_co_u32_e32 v20, vcc, 0x9100, v18
	s_nop 1
	v_addc_co_u32_e32 v21, vcc, 0, v19, vcc
	global_store_short v[20:21], v35, off
	v_mul_f32_e32 v20, v24, v34
	v_cvt_pk_bf16_f32 v35, v20, s0
	v_add_co_u32_e32 v20, vcc, 0x12200, v18
	s_nop 1
	v_addc_co_u32_e32 v21, vcc, 0, v19, vcc
	global_store_short v[20:21], v35, off
	v_mul_f32_e32 v20, v25, v34
	v_add_co_u32_e32 v18, vcc, 0x1b300, v18
	v_cvt_pk_bf16_f32 v20, v20, s0
	s_nop 0
	v_addc_co_u32_e32 v19, vcc, 0, v19, vcc
	global_store_short v[18:19], v20, off
	s_andn2_saveexec_b64 s[0:1], s[0:1]
	s_cbranch_execz .LBB0_354

.LBB0_400:
	s_mul_i32 s11, s8, 0x488000
	v_mov_b32_e32 v71, v1
	s_add_u32 s12, s9, s11
	s_addc_u32 s13, s10, 0
	v_mul_u32_u24_e32 v18, 0x9100, v70
	v_mov_b32_e32 v19, v1
	v_lshl_add_u64 v[18:19], s[12:13], 0, v[18:19]
	s_waitcnt lgkmcnt(0)
	v_mul_f32_e32 v20, v26, v34
	v_lshl_add_u64 v[18:19], v[98:99], 1, v[18:19]
	v_cvt_pk_bf16_f32 v20, v20, s0
	global_store_short v[18:19], v20, off
	v_mul_f32_e32 v20, v27, v34
	v_cvt_pk_bf16_f32 v22, v20, s0
	v_add_co_u32_e32 v20, vcc, 0x9100, v18
	s_nop 1
	v_addc_co_u32_e32 v21, vcc, 0, v19, vcc
	global_store_short v[20:21], v22, off
	v_mul_f32_e32 v20, v28, v34
	v_cvt_pk_bf16_f32 v22, v20, s0
	v_add_co_u32_e32 v20, vcc, 0x12200, v18
	s_nop 1
	v_addc_co_u32_e32 v21, vcc, 0, v19, vcc
	global_store_short v[20:21], v22, off
	v_mul_f32_e32 v20, v29, v34
	v_add_co_u32_e32 v18, vcc, 0x1b300, v18
	v_cvt_pk_bf16_f32 v20, v20, s0
	s_nop 0
	v_addc_co_u32_e32 v19, vcc, 0, v19, vcc
	global_store_short v[18:19], v20, off
	s_andn2_saveexec_b64 s[0:1], s[0:1]
	s_cbranch_execz .LBB0_356

.LBB0_402:
	s_mul_i32 s11, s8, 0x488000
	v_mov_b32_e32 v67, v1
	s_add_u32 s12, s9, s11
	s_addc_u32 s13, s10, 0
	v_mul_u32_u24_e32 v18, 0x9100, v66
	v_mov_b32_e32 v19, v1
	v_lshl_add_u64 v[18:19], s[12:13], 0, v[18:19]
	s_waitcnt lgkmcnt(0)
	v_mul_f32_e32 v20, v30, v34
	v_lshl_add_u64 v[18:19], v[98:99], 1, v[18:19]
	v_cvt_pk_bf16_f32 v20, v20, s0
	global_store_short v[18:19], v20, off
	v_mul_f32_e32 v20, v31, v34
	v_cvt_pk_bf16_f32 v22, v20, s0
	v_add_co_u32_e32 v20, vcc, 0x9100, v18
	s_nop 1
	v_addc_co_u32_e32 v21, vcc, 0, v19, vcc
	global_store_short v[20:21], v22, off
	v_mul_f32_e32 v20, v32, v34
	v_cvt_pk_bf16_f32 v22, v20, s0
	v_add_co_u32_e32 v20, vcc, 0x12200, v18
	s_nop 1
	v_addc_co_u32_e32 v21, vcc, 0, v19, vcc
	global_store_short v[20:21], v22, off
	v_mul_f32_e32 v20, v33, v34
	v_add_co_u32_e32 v18, vcc, 0x1b300, v18
	v_cvt_pk_bf16_f32 v20, v20, s0
	s_nop 0
	v_addc_co_u32_e32 v19, vcc, 0, v19, vcc
	global_store_short v[18:19], v20, off
	s_andn2_saveexec_b64 s[0:1], s[0:1]
	s_cbranch_execnz .LBB0_358
	s_branch .LBB0_359
.LBB0_403:
	s_mul_i32 s11, s8, 0x488000
	v_mov_b32_e32 v69, v1
	s_add_u32 s12, s9, s11
	s_addc_u32 s13, s10, 0
	v_mul_u32_u24_e32 v20, 0x9100, v68
	v_mov_b32_e32 v21, v1
	v_lshl_add_u64 v[20:21], s[12:13], 0, v[20:21]
	s_waitcnt lgkmcnt(0)
	v_mul_f32_e32 v19, v2, v18
	v_lshl_add_u64 v[20:21], v[82:83], 1, v[20:21]
	v_cvt_pk_bf16_f32 v19, v19, s0
	global_store_short v[20:21], v19, off
	v_mul_f32_e32 v19, v3, v18
	v_add_co_u32_e32 v22, vcc, 0x9100, v20
	v_cvt_pk_bf16_f32 v19, v19, s0
	s_nop 0
	v_addc_co_u32_e32 v23, vcc, 0, v21, vcc
	global_store_short v[22:23], v19, off
	v_mul_f32_e32 v19, v4, v18
	v_add_co_u32_e32 v22, vcc, 0x12200, v20
	v_cvt_pk_bf16_f32 v19, v19, s0
	s_nop 0
	v_addc_co_u32_e32 v23, vcc, 0, v21, vcc
	global_store_short v[22:23], v19, off
	v_mul_f32_e32 v19, v5, v18
	v_add_co_u32_e32 v20, vcc, 0x1b300, v20
	v_cvt_pk_bf16_f32 v19, v19, s0
	s_nop 0
	v_addc_co_u32_e32 v21, vcc, 0, v21, vcc
	global_store_short v[20:21], v19, off
	s_andn2_saveexec_b64 s[0:1], s[0:1]
	s_cbranch_execz .LBB0_361

.LBB0_405:
	s_mul_i32 s11, s8, 0x488000
	v_mov_b32_e32 v73, v1
	s_add_u32 s12, s9, s11
	s_addc_u32 s13, s10, 0
	v_mul_u32_u24_e32 v2, 0x9100, v72
	v_mov_b32_e32 v3, v1
	v_lshl_add_u64 v[2:3], s[12:13], 0, v[2:3]
	s_waitcnt lgkmcnt(0)
	v_mul_f32_e32 v4, v6, v18
	v_lshl_add_u64 v[2:3], v[82:83], 1, v[2:3]
	v_cvt_pk_bf16_f32 v4, v4, s0
	global_store_short v[2:3], v4, off
	v_mul_f32_e32 v4, v7, v18
	v_cvt_pk_bf16_f32 v19, v4, s0
	v_add_co_u32_e32 v4, vcc, 0x9100, v2
	s_nop 1
	v_addc_co_u32_e32 v5, vcc, 0, v3, vcc
	global_store_short v[4:5], v19, off
	v_mul_f32_e32 v4, v8, v18
	v_cvt_pk_bf16_f32 v19, v4, s0
	v_add_co_u32_e32 v4, vcc, 0x12200, v2
	s_nop 1
	v_addc_co_u32_e32 v5, vcc, 0, v3, vcc
	global_store_short v[4:5], v19, off
	v_mul_f32_e32 v4, v9, v18
	v_add_co_u32_e32 v2, vcc, 0x1b300, v2
	v_cvt_pk_bf16_f32 v4, v4, s0
	s_nop 0
	v_addc_co_u32_e32 v3, vcc, 0, v3, vcc
	global_store_short v[2:3], v4, off
	s_andn2_saveexec_b64 s[0:1], s[0:1]
	s_cbranch_execz .LBB0_363

.LBB0_407:
	s_mul_i32 s11, s8, 0x488000
	v_mov_b32_e32 v71, v1
	s_add_u32 s12, s9, s11
	s_addc_u32 s13, s10, 0
	v_mul_u32_u24_e32 v2, 0x9100, v70
	v_mov_b32_e32 v3, v1
	v_lshl_add_u64 v[2:3], s[12:13], 0, v[2:3]
	s_waitcnt lgkmcnt(0)
	v_mul_f32_e32 v4, v10, v18
	v_lshl_add_u64 v[2:3], v[82:83], 1, v[2:3]
	v_cvt_pk_bf16_f32 v4, v4, s0
	global_store_short v[2:3], v4, off
	v_mul_f32_e32 v4, v11, v18
	v_cvt_pk_bf16_f32 v6, v4, s0
	v_add_co_u32_e32 v4, vcc, 0x9100, v2
	s_nop 1
	v_addc_co_u32_e32 v5, vcc, 0, v3, vcc
	global_store_short v[4:5], v6, off
	v_mul_f32_e32 v4, v12, v18
	v_cvt_pk_bf16_f32 v6, v4, s0
	v_add_co_u32_e32 v4, vcc, 0x12200, v2
	s_nop 1
	v_addc_co_u32_e32 v5, vcc, 0, v3, vcc
	global_store_short v[4:5], v6, off
	v_mul_f32_e32 v4, v13, v18
	v_add_co_u32_e32 v2, vcc, 0x1b300, v2
	v_cvt_pk_bf16_f32 v4, v4, s0
	s_nop 0
	v_addc_co_u32_e32 v3, vcc, 0, v3, vcc
	global_store_short v[2:3], v4, off
	s_andn2_saveexec_b64 s[0:1], s[0:1]
	s_cbranch_execz .LBB0_365

.LBB0_409:
	s_mul_i32 s2, s8, 0x488000
	v_mov_b32_e32 v67, v1
	s_add_u32 s2, s9, s2
	s_addc_u32 s3, s10, 0
	v_mul_u32_u24_e32 v2, 0x9100, v66
	v_mov_b32_e32 v3, v1
	v_lshl_add_u64 v[2:3], s[2:3], 0, v[2:3]
	s_waitcnt lgkmcnt(0)
	v_mul_f32_e32 v0, v14, v18
	v_lshl_add_u64 v[2:3], v[82:83], 1, v[2:3]
	v_cvt_pk_bf16_f32 v0, v0, s0
	global_store_short v[2:3], v0, off
	v_mul_f32_e32 v0, v15, v18
	v_add_co_u32_e32 v4, vcc, 0x9100, v2
	v_cvt_pk_bf16_f32 v0, v0, s0
	s_nop 0
	v_addc_co_u32_e32 v5, vcc, 0, v3, vcc
	global_store_short v[4:5], v0, off
	v_mul_f32_e32 v0, v16, v18
	v_add_co_u32_e32 v4, vcc, 0x12200, v2
	v_cvt_pk_bf16_f32 v0, v0, s0
	s_nop 0
	v_addc_co_u32_e32 v5, vcc, 0, v3, vcc
	global_store_short v[4:5], v0, off
	v_mul_f32_e32 v0, v17, v18
	v_add_co_u32_e32 v2, vcc, 0x1b300, v2
	v_cvt_pk_bf16_f32 v0, v0, s0
	s_nop 0
	v_addc_co_u32_e32 v3, vcc, 0, v3, vcc
	global_store_short v[2:3], v0, off
	s_andn2_saveexec_b64 s[0:1], s[0:1]
	s_cbranch_execz .LBB0_367

; DI void mla_attn_item(const Params& P, int hd, int b, char* smem) {
;     ...
;   const int q = 128 * b + 32 * wq + lq;
;   bf16x8 qf[12];
;   {
;     const float* qp = qraw + (size_t)q * 768 + hd * 192 + 8 * h;
;     const float sc = 0.07216878364870322f * LOG2E;
; #pragma unroll
;     for (int s = 0; s < 8; ++s) { const f32x4 a = *(const f32x4*)(qp + 16 * s), c = *(const f32x4*)(qp + 16 * s + 4);
;       qf[s] = pack8(a.x * sc, a.y * sc, a.z * sc, a.w * sc, c.x * sc, c.y * sc, c.z * sc, c.w * sc); }
;     const double pq = (double)P.pos[q];
; #pragma unroll
;     for (int s2 = 0; s2 < 2; ++s2) {
;       const f32x4 a0 = *(const f32x4*)(qp + 128 + 16 * s2), a1 = *(const f32x4*)(qp + 128 + 16 * s2 + 4);
;       const f32x4 b0 = *(const f32x4*)(qp + 160 + 16 * s2), b1 = *(const f32x4*)(qp + 160 + 16 * s2 + 4);
;       float x1[8] = {a0.x, a0.y, a0.z, a0.w, a1.x, a1.y, a1.z, a1.w}, x2[8] = {b0.x, b0.y, b0.z, b0.w, b1.x, b1.y, b1.z, b1.w}, o1[8], o2[8];
; #pragma unroll
;       for (int j = 0; j < 8; ++j) { double fr = pq * kInvFreq2Pi[16 * s2 + 8 * h + j]; fr -= floor(fr); const float ff = (float)fr;
;         const float sn = __builtin_amdgcn_sinf(ff), cs = __builtin_amdgcn_cosf(ff);
;         o1[j] = (x1[j] * cs - x2[j] * sn) * sc; o2[j] = (x2[j] * cs + x1[j] * sn) * sc; }
;       qf[8 + s2] = pack8(o1[0], o1[1], o1[2], o1[3], o1[4], o1[5], o1[6], o1[7]);
;       qf[10 + s2] = pack8(o2[0], o2[1], o2[2], o2[3], o2[4], o2[5], o2[6], o2[7]);
;     }
;   }
;   constexpr int KST = 64 * 400, VST = 128 * 144, STG = KST + VST;
;   f32x16 O[4];
; #pragma unroll
;   for (int i = 0; i < 4; ++i)
; #pragma unroll
;     for (int r = 0; r < 16; ++r) O[i][r] = 0.f;
;   float m_i = -1e30f, l_i = 0.f;
;   const int nt = 2 * b + 2;
;   u32x4 rk0[3], rv0[2], rk1[3], rv1[2];
;   const int vrow = tid >> 3, vcc = tid & 7;
;   const int ntl = nt - 1;
.LBB0_640:
	s_and_b64 vcc, exec, s[2:3]
	s_cbranch_vccz .LBB0_660
	v_mov_b32_e32 v187, v206
	global_load_dwordx2 v[184:185], v1, s[40:41] offset:1224
	global_load_dwordx2 v[2:3], v1, s[40:41] offset:1040
	s_add_i32 s2, s96, -16
	s_lshr_b32 s8, s2, 2
	v_bfe_u32 v209, v187, 6, 2
	s_sub_i32 s9, 0x7f, s8
	v_lshlrev_b32_e32 v39, 5, v209
	v_and_b32_e32 v38, 31, v187
	v_lshl_or_b32 v213, s9, 7, v39
	s_and_b32 s97, s96, 3
	v_or_b32_e32 v186, v213, v38
	s_movk_i32 s4, 0xc00
	s_mov_b32 s3, s63
	s_mul_i32 s2, s97, 0x300
	v_and_b32_e32 v0, 32, v187
	v_bfe_u32 v40, v187, 5, 1
	v_lshlrev_b32_e32 v41, 6, v40
	s_mul_i32 s62, s97, 0x600000
	v_ashrrev_i32_e32 v221, 8, v187
	v_lshlrev_b32_e32 v216, 2, v40
	v_lshlrev_b32_e32 v222, 6, v221
	s_movk_i32 s61, 0x100
	v_and_b32_e32 v215, 63, v187
	v_lshrrev_b32_e32 v214, 6, v187
	v_mov_b32_e32 v229, 0xf149f2ca
	v_mov_b32_e32 v212, 0
	s_mov_b32 s60, -2
	s_waitcnt vmcnt(0)
	v_mad_u64_u32 v[4:5], s[4:5], v186, s4, v[184:185]
	v_lshl_add_u64 v[4:5], v[4:5], 0, s[2:3]
	v_lshl_add_u64 v[4:5], v[4:5], 0, v[0:1]
	s_mov_b32 s2, 0xa2e8000
	v_add_co_u32_e32 v6, vcc, s2, v4
	s_mov_b64 s[2:3], 0xa2e8000
	v_lshlrev_b32_e32 v0, 2, v186
	v_addc_co_u32_e32 v7, vcc, 0, v5, vcc
	v_lshl_add_u64 v[18:19], v[4:5], 0, s[2:3]
	v_lshl_add_u64 v[2:3], v[2:3], 0, v[0:1]
	global_load_dwordx4 v[20:23], v[6:7], off
	global_load_dwordx4 v[24:27], v[18:19], off offset:16
	global_load_dwordx4 v[28:31], v[18:19], off offset:64
	global_load_dwordx4 v[32:35], v[18:19], off offset:80
	global_load_dwordx4 v[42:45], v[18:19], off offset:128
	global_load_dwordx4 v[46:49], v[18:19], off offset:144
	global_load_dwordx4 v[50:53], v[18:19], off offset:192
	global_load_dwordx4 v[54:57], v[18:19], off offset:208
	global_load_dwordx4 v[58:61], v[18:19], off offset:256
	global_load_dwordx4 v[62:65], v[18:19], off offset:272
	global_load_dwordx4 v[66:69], v[18:19], off offset:320
	global_load_dwordx4 v[70:73], v[18:19], off offset:336
	global_load_dwordx4 v[74:77], v[18:19], off offset:384
	global_load_dwordx4 v[78:81], v[18:19], off offset:400
	global_load_dwordx4 v[82:85], v[18:19], off offset:448
	global_load_dword v0, v[2:3], off
	s_getpc_b64 s[4:5]
	s_add_u32 s4, s4, kInvFreq2Pi@rel32@lo+4
	s_addc_u32 s5, s5, kInvFreq2Pi@rel32@hi+12
	global_load_dwordx4 v[86:89], v[18:19], off offset:464
	global_load_dwordx4 v[90:93], v41, s[4:5] offset:16
	global_load_dwordx4 v[128:131], v41, s[4:5]
	s_getpc_b64 s[2:3]
	s_add_u32 s2, s2, kInvFreq2Pi@rel32@lo+132
	s_addc_u32 s3, s3, kInvFreq2Pi@rel32@hi+140
	global_load_dwordx4 v[132:135], v41, s[4:5] offset:48
	global_load_dwordx4 v[136:139], v41, s[4:5] offset:32
	global_load_dwordx4 v[10:13], v41, s[2:3] offset:16
	global_load_dwordx4 v[14:17], v41, s[2:3]
	global_load_dwordx4 v[140:143], v[18:19], off offset:512
	global_load_dwordx4 v[144:147], v[18:19], off offset:528
	global_load_dwordx4 v[148:151], v[18:19], off offset:656
	global_load_dwordx4 v[152:155], v[18:19], off offset:640
	global_load_dwordx4 v[2:5], v[18:19], off offset:592
	global_load_dwordx4 v[6:9], v[18:19], off offset:720
	v_lshl_add_u64 v[36:37], v[184:185], 0, s[62:63]
	s_mul_i32 s62, s97, 0x488000
	s_mov_b64 s[4:5], 0xd2e8000
	v_lshl_add_u64 v[188:189], v[36:37], 0, s[4:5]
	s_lshl_b32 s56, s9, 1
	s_or_b32 s57, s56, 1
	s_waitcnt vmcnt(0) lgkmcnt(0)
	v_pk_mul_f32 v[24:25], v[24:25], s[54:55] op_sel_hi:[1,0]
	v_pk_mul_f32 v[26:27], v[26:27], s[54:55] op_sel_hi:[1,0]
	v_pk_mul_f32 v[94:95], v[34:35], s[54:55] op_sel_hi:[1,0]
	v_pk_mul_f32 v[28:29], v[28:29], s[54:55] op_sel_hi:[1,0]
	v_pk_mul_f32 v[30:31], v[30:31], s[54:55] op_sel_hi:[1,0]
	v_cvt_pk_bf16_f32 v98, v24, v25
	v_cvt_pk_bf16_f32 v99, v26, v27
	v_cvt_pk_bf16_f32 v100, v28, v29
	v_cvt_pk_bf16_f32 v101, v30, v31
	v_pk_mul_f32 v[46:47], v[46:47], s[54:55] op_sel_hi:[1,0]
	v_pk_mul_f32 v[32:33], v[32:33], s[54:55] op_sel_hi:[1,0]
	v_cvt_pk_bf16_f32 v106, v46, v47
	v_pk_mul_f32 v[20:21], v[20:21], s[54:55] op_sel_hi:[1,0]
	v_pk_mul_f32 v[22:23], v[22:23], s[54:55] op_sel_hi:[1,0]
	v_cvt_f64_i32_e32 v[34:35], v0
	v_cvt_pk_bf16_f32 v96, v20, v21
	v_cvt_pk_bf16_f32 v97, v22, v23
	v_mul_f64 v[20:21], v[128:129], v[34:35]
	v_mul_f64 v[22:23], v[130:131], v[34:35]
	v_mul_f64 v[24:25], v[90:91], v[34:35]
	v_mul_f64 v[26:27], v[92:93], v[34:35]
	v_mul_f64 v[28:29], v[136:137], v[34:35]
	v_mul_f64 v[30:31], v[138:139], v[34:35]
	v_floor_f64_e32 v[20:21], v[20:21]
	v_floor_f64_e32 v[22:23], v[22:23]
	v_floor_f64_e32 v[24:25], v[24:25]
	v_floor_f64_e32 v[26:27], v[26:27]
	v_floor_f64_e32 v[28:29], v[28:29]
	v_floor_f64_e32 v[30:31], v[30:31]
	v_fma_f64 v[20:21], v[128:129], v[34:35], -v[20:21]
	v_fma_f64 v[22:23], v[130:131], v[34:35], -v[22:23]
	v_fma_f64 v[24:25], v[90:91], v[34:35], -v[24:25]
	v_fma_f64 v[26:27], v[92:93], v[34:35], -v[26:27]
	v_fma_f64 v[28:29], v[136:137], v[34:35], -v[28:29]
	v_fma_f64 v[30:31], v[138:139], v[34:35], -v[30:31]
	v_cvt_f32_f64_e32 v0, v[20:21]
	v_cvt_f32_f64_e32 v23, v[22:23]
	v_cvt_f32_f64_e32 v25, v[24:25]
	v_cvt_f32_f64_e32 v27, v[26:27]
	v_cvt_f32_f64_e32 v46, v[28:29]
	v_cvt_f32_f64_e32 v47, v[30:31]
	v_sin_f32_e32 v20, v0
	v_sin_f32_e32 v21, v23
	v_sin_f32_e32 v24, v25
	v_cos_f32_e32 v26, v25
	v_sin_f32_e32 v25, v27
	v_cos_f32_e32 v22, v0
	v_cos_f32_e32 v23, v23
	v_cos_f32_e32 v27, v27
	v_sin_f32_e32 v30, v46
	v_sin_f32_e32 v31, v47
	v_cos_f32_e32 v46, v46
	v_cos_f32_e32 v47, v47
	v_pk_mul_f32 v[48:49], v[48:49], s[54:55] op_sel_hi:[1,0]
	v_cvt_pk_bf16_f32 v102, v32, v33
	v_pk_mul_f32 v[28:29], v[152:153], v[20:21]
	v_pk_mul_f32 v[20:21], v[140:141], v[20:21]
	v_pk_mul_f32 v[32:33], v[154:155], v[24:25]
	v_pk_mul_f32 v[24:25], v[142:143], v[24:25]
; DI void mla_attn_item(const Params& P, int hd, int b, char* smem) {
;     ...
;     const double pq = (double)P.pos[q];
; #pragma unroll
;     for (int s2 = 0; s2 < 2; ++s2) {
;       const f32x4 a0 = *(const f32x4*)(qp + 128 + 16 * s2), a1 = *(const f32x4*)(qp + 128 + 16 * s2 + 4);
;       const f32x4 b0 = *(const f32x4*)(qp + 160 + 16 * s2), b1 = *(const f32x4*)(qp + 160 + 16 * s2 + 4);
;       float x1[8] = {a0.x, a0.y, a0.z, a0.w, a1.x, a1.y, a1.z, a1.w}, x2[8] = {b0.x, b0.y, b0.z, b0.w, b1.x, b1.y, b1.z, b1.w}, o1[8], o2[8];
; #pragma unroll
;       for (int j = 0; j < 8; ++j) { double fr = pq * kInvFreq2Pi[16 * s2 + 8 * h + j]; fr -= floor(fr); const float ff = (float)fr;
;         const float sn = __builtin_amdgcn_sinf(ff), cs = __builtin_amdgcn_cosf(ff);
;         o1[j] = (x1[j] * cs - x2[j] * sn) * sc; o2[j] = (x2[j] * cs + x1[j] * sn) * sc; }
;       qf[8 + s2] = pack8(o1[0], o1[1], o1[2], o1[3], o1[4], o1[5], o1[6], o1[7]);
;       qf[10 + s2] = pack8(o2[0], o2[1], o2[2], o2[3], o2[4], o2[5], o2[6], o2[7]);
;     }
;   }
;   constexpr int KST = 64 * 400, VST = 128 * 144, STG = KST + VST;
;   f32x16 O[4];
; #pragma unroll
;   for (int i = 0; i < 4; ++i)
; #pragma unroll
;     for (int r = 0; r < 16; ++r) O[i][r] = 0.f;
;   float m_i = -1e30f, l_i = 0.f;
;   const int nt = 2 * b + 2;
;   u32x4 rk0[3], rv0[2], rk1[3], rv1[2];
;   const int vrow = tid >> 3, vcc = tid & 7;
;   const int ntl = nt - 1;
	v_pk_mul_f32 v[42:43], v[42:43], s[54:55] op_sel_hi:[1,0]
	v_pk_mul_f32 v[44:45], v[44:45], s[54:55] op_sel_hi:[1,0]
	v_cvt_pk_bf16_f32 v107, v48, v49
	v_pk_fma_f32 v[28:29], v[140:141], v[22:23], v[28:29] neg_lo:[0,0,1] neg_hi:[0,0,1]
	v_pk_fma_f32 v[20:21], v[152:153], v[22:23], v[20:21]
	v_pk_fma_f32 v[22:23], v[142:143], v[26:27], v[32:33] neg_lo:[0,0,1] neg_hi:[0,0,1]
	v_pk_fma_f32 v[24:25], v[154:155], v[26:27], v[24:25]
	v_pk_mul_f32 v[48:49], v[148:149], v[30:31]
	v_pk_mul_f32 v[52:53], v[52:53], s[54:55] op_sel_hi:[1,0]
	v_cvt_pk_bf16_f32 v104, v42, v43
	v_cvt_pk_bf16_f32 v105, v44, v45
	v_pk_mul_f32 v[32:33], v[28:29], s[54:55] op_sel_hi:[1,0]
	v_pk_mul_f32 v[42:43], v[22:23], s[54:55] op_sel_hi:[1,0]
	v_pk_mul_f32 v[44:45], v[24:25], s[54:55] op_sel_hi:[1,0]
	global_load_dwordx4 v[22:25], v[18:19], off offset:704
	global_load_dwordx4 v[26:29], v[18:19], off offset:576
	v_pk_fma_f32 v[18:19], v[144:145], v[46:47], v[48:49] neg_lo:[0,0,1] neg_hi:[0,0,1]
	v_mul_f64 v[48:49], v[132:133], v[34:35]
	v_cvt_pk_bf16_f32 v109, v52, v53
	v_floor_f64_e32 v[48:49], v[48:49]
	v_mul_f64 v[52:53], v[134:135], v[34:35]
	v_fma_f64 v[48:49], v[132:133], v[34:35], -v[48:49]
	v_floor_f64_e32 v[52:53], v[52:53]
	v_pk_mul_f32 v[50:51], v[50:51], s[54:55] op_sel_hi:[1,0]
	v_cvt_f32_f64_e32 v0, v[48:49]
	v_fma_f64 v[52:53], v[134:135], v[34:35], -v[52:53]
	v_cvt_pk_bf16_f32 v108, v50, v51
	v_sin_f32_e32 v48, v0
	v_cos_f32_e32 v50, v0
	v_cvt_f32_f64_e32 v0, v[52:53]
	v_sin_f32_e32 v49, v0
	v_cos_f32_e32 v51, v0
	v_pk_mul_f32 v[30:31], v[144:145], v[30:31]
	v_pk_mul_f32 v[62:63], v[62:63], s[54:55] op_sel_hi:[1,0]
	v_pk_fma_f32 v[30:31], v[148:149], v[46:47], v[30:31]
	v_cvt_pk_bf16_f32 v114, v62, v63
	v_pk_mul_f32 v[62:63], v[30:31], s[54:55] op_sel_hi:[1,0]
	v_pk_mul_f32 v[30:31], v[150:151], v[48:49]
	v_pk_mul_f32 v[66:67], v[66:67], s[54:55] op_sel_hi:[1,0]
	v_pk_fma_f32 v[30:31], v[146:147], v[50:51], v[30:31] neg_lo:[0,0,1] neg_hi:[0,0,1]
	v_pk_mul_f32 v[20:21], v[20:21], s[54:55] op_sel_hi:[1,0]
	v_pk_mul_f32 v[18:19], v[18:19], s[54:55] op_sel_hi:[1,0]
	v_pk_mul_f32 v[30:31], v[30:31], s[54:55] op_sel_hi:[1,0]
	v_cvt_pk_bf16_f32 v129, v42, v43
	v_mul_f64 v[42:43], v[14:15], v[34:35]
	v_pk_mul_f32 v[68:69], v[68:69], s[54:55] op_sel_hi:[1,0]
	v_cvt_pk_bf16_f32 v116, v66, v67
	v_cvt_pk_bf16_f32 v128, v32, v33
	v_cvt_pk_bf16_f32 v130, v18, v19
	v_cvt_pk_bf16_f32 v131, v30, v31
	v_cvt_pk_bf16_f32 v132, v20, v21
	global_load_dwordx4 v[18:21], v41, s[2:3] offset:48
	global_load_dwordx4 v[30:33], v41, s[2:3] offset:32
	v_floor_f64_e32 v[66:67], v[42:43]
	v_lshl_add_u64 v[42:43], v[184:185], 0, s[62:63]
	s_mov_b64 s[2:3], 0xeae8000
	v_cvt_pk_bf16_f32 v117, v68, v69
	v_lshl_add_u64 v[68:69], v[42:43], 0, s[2:3]
	s_mov_b32 s3, 0x2aaaaaab
	v_mul_hi_i32 v0, v187, s3
	v_lshrrev_b32_e32 v41, 31, v0
	v_ashrrev_i32_e32 v0, 2, v0
	v_add_u32_e32 v41, v0, v41
	v_pk_mul_f32 v[86:87], v[86:87], s[54:55] op_sel_hi:[1,0]
	v_mul_lo_u32 v0, v41, 24
	v_cvt_pk_bf16_f32 v126, v86, v87
	v_sub_u32_e32 v86, v187, v0
	v_add_u32_e32 v0, 0x200, v187
	v_cvt_pk_bf16_f32 v133, v44, v45
	v_mul_hi_i32 v44, v0, s3
	v_lshrrev_b32_e32 v45, 31, v44
	v_ashrrev_i32_e32 v44, 2, v44
	v_add_u32_e32 v87, v44, v45
	v_pk_mul_f32 v[88:89], v[88:89], s[54:55] op_sel_hi:[1,0]
	v_mul_lo_u32 v44, v87, 24
	v_cvt_pk_bf16_f32 v127, v88, v89
	v_pk_mul_f32 v[46:47], v[146:147], v[48:49]
	v_sub_u32_e32 v88, v0, v44
	v_add_u32_e32 v0, 0x400, v187
	v_pk_fma_f32 v[46:47], v[150:151], v[50:51], v[46:47]
	v_mul_hi_i32 v50, v0, s3
	v_lshrrev_b32_e32 v51, 31, v50
	v_ashrrev_i32_e32 v50, 2, v50
	v_add_u32_e32 v89, v50, v51
	s_movk_i32 s2, 0xc0
	v_mul_lo_u32 v50, v89, 24
	v_pk_mul_f32 v[82:83], v[82:83], s[54:55] op_sel_hi:[1,0]
	v_mul_lo_u32 v190, v41, s2
	v_mul_lo_u32 v194, v87, s2
	v_sub_u32_e32 v90, v0, v50
	v_mul_lo_u32 v198, v89, s2
	v_pk_mul_f32 v[70:71], v[70:71], s[54:55] op_sel_hi:[1,0]
	v_pk_mul_f32 v[74:75], v[74:75], s[54:55] op_sel_hi:[1,0]
	v_pk_mul_f32 v[78:79], v[78:79], s[54:55] op_sel_hi:[1,0]
	v_cvt_pk_bf16_f32 v124, v82, v83
	v_ashrrev_i32_e32 v191, 31, v190
	v_lshlrev_b32_e32 v192, 3, v86
	v_ashrrev_i32_e32 v195, 31, v194
	v_lshlrev_b32_e32 v196, 3, v88
	v_ashrrev_i32_e32 v199, 31, v198
	v_lshlrev_b32_e32 v200, 3, v90
	v_ashrrev_i32_e32 v82, 3, v187
	v_lshlrev_b32_e32 v0, 4, v187
	v_pk_mul_f32 v[72:73], v[72:73], s[54:55] op_sel_hi:[1,0]
	v_pk_mul_f32 v[76:77], v[76:77], s[54:55] op_sel_hi:[1,0]
	v_pk_mul_f32 v[80:81], v[80:81], s[54:55] op_sel_hi:[1,0]
	v_cvt_pk_bf16_f32 v118, v70, v71
	v_cvt_pk_bf16_f32 v120, v74, v75
	v_cvt_pk_bf16_f32 v122, v78, v79
	v_lshlrev_b64 v[70:71], 1, v[190:191]
	v_ashrrev_i32_e32 v193, 31, v192
	v_lshlrev_b64 v[74:75], 1, v[194:195]
	v_ashrrev_i32_e32 v197, 31, v196
	v_lshlrev_b64 v[78:79], 1, v[198:199]
	v_ashrrev_i32_e32 v201, 31, v200
	v_and_b32_e32 v0, 0x70, v0
	v_ashrrev_i32_e32 v83, 31, v82
	v_pk_mul_f32 v[54:55], v[54:55], s[54:55] op_sel_hi:[1,0]
	v_pk_mul_f32 v[64:65], v[64:65], s[54:55] op_sel_hi:[1,0]
	v_cvt_pk_bf16_f32 v119, v72, v73
	v_cvt_pk_bf16_f32 v121, v76, v77
	v_cvt_pk_bf16_f32 v123, v80, v81
	v_lshl_add_u64 v[42:43], v[188:189], 0, v[70:71]
	v_lshlrev_b64 v[72:73], 1, v[192:193]
	v_lshl_add_u64 v[44:45], v[188:189], 0, v[74:75]
	v_lshlrev_b64 v[76:77], 1, v[196:197]
	v_lshl_add_u64 v[50:51], v[188:189], 0, v[78:79]
	v_lshlrev_b64 v[80:81], 1, v[200:201]
	v_lshl_add_u64 v[202:203], v[68:69], 0, v[0:1]
	v_mul_u32_u24_e32 v204, 0x9100, v82
	v_mov_b32_e32 v205, v1
	s_mov_b64 s[2:3], 0x244000
	v_pk_mul_f32 v[56:57], v[56:57], s[54:55] op_sel_hi:[1,0]
	v_pk_mul_f32 v[58:59], v[58:59], s[54:55] op_sel_hi:[1,0]
	v_cvt_pk_bf16_f32 v110, v54, v55
	v_cvt_pk_bf16_f32 v115, v64, v65
	v_pk_mul_f32 v[64:65], v[46:47], s[54:55] op_sel_hi:[1,0]
	v_lshl_add_u64 v[42:43], v[42:43], 0, v[72:73]
	v_lshl_add_u64 v[46:47], v[44:45], 0, v[76:77]
	v_lshl_add_u64 v[50:51], v[50:51], 0, v[80:81]
	v_lshl_add_u64 v[54:55], v[202:203], 0, v[204:205]
	v_lshl_add_u64 v[210:211], v[204:205], 0, s[2:3]
	v_pk_mul_f32 v[60:61], v[60:61], s[54:55] op_sel_hi:[1,0]
	v_cvt_pk_bf16_f32 v111, v56, v57
	v_cvt_pk_bf16_f32 v112, v58, v59
	global_load_dwordx4 v[42:45], v[42:43], off
	s_nop 0
	global_load_dwordx4 v[46:49], v[46:47], off
	s_nop 0
	global_load_dwordx4 v[50:53], v[50:51], off
	s_nop 0
	global_load_dwordx4 v[54:57], v[54:55], off
	v_lshl_add_u64 v[58:59], v[202:203], 0, v[210:211]
	v_cvt_pk_bf16_f32 v113, v60, v61
	global_load_dwordx4 v[58:61], v[58:59], off
	v_pk_mul_f32 v[84:85], v[84:85], s[54:55] op_sel_hi:[1,0]
	v_fma_f64 v[14:15], v[14:15], v[34:35], -v[66:67]
	v_cvt_pk_bf16_f32 v125, v84, v85
	v_mul_f64 v[84:85], v[16:17], v[34:35]
	v_floor_f64_e32 v[84:85], v[84:85]
	v_fma_f64 v[16:17], v[16:17], v[34:35], -v[84:85]
	v_cvt_f32_f64_e32 v15, v[14:15]
	v_cvt_f32_f64_e32 v16, v[16:17]
	v_sin_f32_e32 v14, v15
	v_cos_f32_e32 v66, v15
	v_sin_f32_e32 v15, v16
	v_cos_f32_e32 v67, v16
	v_cvt_pk_bf16_f32 v134, v62, v63
	v_mul_f64 v[62:63], v[12:13], v[34:35]
	s_waitcnt vmcnt(0) lgkmcnt(0)
; #define AT_LOAD(RK, RV, T) { const size_t ko_ = (size_t)(T) * 64 * 192; const int vo_ = (T) * 64; \
;     _Pragma("unroll") for (int i = 0; i < 3; ++i) { const int id = tid + NT * i, row = id / 24, cc = id % 24; RK[i] = *(const u32x4*)(Kg + ko_ + row * 192 + cc * 8); } \
;     _Pragma("unroll") for (int i = 0; i < 2; ++i) RV[i] = *(const u32x4*)(Vg + (size_t)(vrow + 64 * i) * S_ + vo_ + vcc * 8); }
; #define AT_WRITE(RK, RV, ST) { char* dK = smem + (ST) * STG; \
;     _Pragma("unroll") for (int i = 0; i < 3; ++i) { const int id = tid + NT * i, row = id / 24, cc = id % 24; *(u32x4*)(dK + row * 400 + cc * 16) = RK[i]; } \
;     _Pragma("unroll") for (int i = 0; i < 2; ++i) *(u32x4*)(dK + KST + (vrow + 64 * i) * 144 + vcc * 16) = RV[i]; }
; DI void mla_attn_item(const Params& P, int hd, int b, char* smem) {
;     ...
;       for (int j = 0; j < 8; ++j) { double fr = pq * kInvFreq2Pi[16 * s2 + 8 * h + j]; fr -= floor(fr); const float ff = (float)fr;
;         const float sn = __builtin_amdgcn_sinf(ff), cs = __builtin_amdgcn_cosf(ff);
;         o1[j] = (x1[j] * cs - x2[j] * sn) * sc; o2[j] = (x2[j] * cs + x1[j] * sn) * sc; }
;       qf[8 + s2] = pack8(o1[0], o1[1], o1[2], o1[3], o1[4], o1[5], o1[6], o1[7]);
;       qf[10 + s2] = pack8(o2[0], o2[1], o2[2], o2[3], o2[4], o2[5], o2[6], o2[7]);
;     ...
;   f32x16 O[4];
; #pragma unroll
;   for (int i = 0; i < 4; ++i)
; #pragma unroll
;     for (int r = 0; r < 16; ++r) O[i][r] = 0.f;
;   float m_i = -1e30f, l_i = 0.f;
;   const int nt = 2 * b + 2;
;   u32x4 rk0[3], rv0[2], rk1[3], rv1[2];
;   const int vrow = tid >> 3, vcc = tid & 7;
;   const int ntl = nt - 1;
;     ...
;   AT_LOAD(rk0, rv0, 0);
;   AT_LOAD(rk1, rv1, 1);
;   AT_WRITE(rk0, rv0, 0);
;   AT_LOAD(rk0, rv0, (2 < ntl ? 2 : ntl));
;   __syncthreads();
	v_pk_mul_f32 v[16:17], v[22:23], v[14:15]
	v_pk_mul_f32 v[14:15], v[26:27], v[14:15]
	v_pk_fma_f32 v[16:17], v[26:27], v[66:67], v[16:17] neg_lo:[0,0,1] neg_hi:[0,0,1]
	v_mul_f64 v[26:27], v[10:11], v[34:35]
	v_floor_f64_e32 v[26:27], v[26:27]
	v_floor_f64_e32 v[62:63], v[62:63]
	v_fma_f64 v[10:11], v[10:11], v[34:35], -v[26:27]
	v_fma_f64 v[12:13], v[12:13], v[34:35], -v[62:63]
	v_cvt_f32_f64_e32 v11, v[10:11]
	v_cvt_f32_f64_e32 v12, v[12:13]
	v_sin_f32_e32 v10, v11
	v_cos_f32_e32 v26, v11
	v_sin_f32_e32 v11, v12
	v_cos_f32_e32 v27, v12
	v_pk_fma_f32 v[12:13], v[22:23], v[66:67], v[14:15]
	s_mov_b64 s[2:3], 0xd2ee000
	v_pk_mul_f32 v[14:15], v[24:25], v[10:11]
	v_pk_mul_f32 v[10:11], v[28:29], v[10:11]
	v_pk_fma_f32 v[14:15], v[28:29], v[26:27], v[14:15] neg_lo:[0,0,1] neg_hi:[0,0,1]
	v_pk_fma_f32 v[10:11], v[24:25], v[26:27], v[10:11]
	v_mul_f64 v[26:27], v[32:33], v[34:35]
	v_floor_f64_e32 v[26:27], v[26:27]
	v_fma_f64 v[26:27], v[32:33], v[34:35], -v[26:27]
	v_cvt_f32_f64_e32 v25, v[26:27]
	v_lshl_add_u64 v[26:27], v[36:37], 0, s[2:3]
	v_lshl_add_u64 v[28:29], v[26:27], 0, v[70:71]
	v_lshl_add_u64 v[28:29], v[28:29], 0, v[72:73]
	global_load_dwordx4 v[136:139], v[28:29], off
	v_lshl_add_u64 v[28:29], v[26:27], 0, v[74:75]
	v_lshl_add_u64 v[26:27], v[26:27], 0, v[78:79]
	v_lshl_add_u64 v[28:29], v[28:29], 0, v[76:77]
	v_lshl_add_u64 v[26:27], v[26:27], 0, v[80:81]
	global_load_dwordx4 v[140:143], v[28:29], off
	global_load_dwordx4 v[144:147], v[26:27], off
	v_lshl_add_u64 v[26:27], v[68:69], 0, v[204:205]
	v_lshl_add_u64 v[26:27], v[26:27], 0, v[0:1]
	v_lshl_add_u64 v[28:29], v[68:69], 0, v[210:211]
	s_movk_i32 s3, 0x190
	v_lshl_add_u64 v[28:29], v[28:29], 0, v[0:1]
	global_load_dwordx4 v[148:151], v[26:27], off offset:128
	global_load_dwordx4 v[152:155], v[28:29], off offset:128
	v_mul_lo_u32 v26, v41, s3
	v_lshlrev_b32_e32 v27, 4, v86
	s_movk_i32 s2, 0x90
	v_add_u32_e32 v217, v26, v27
	v_mul_lo_u32 v26, v87, s3
	v_lshlrev_b32_e32 v27, 4, v88
	v_mul_lo_u32 v32, v82, s2
	s_min_u32 s2, s57, 2
	v_add_u32_e32 v218, v26, v27
	v_mul_lo_u32 v26, v89, s3
	v_lshlrev_b32_e32 v27, 4, v90
	s_mul_i32 s62, s2, 0x6000
	v_mul_f64 v[22:23], v[30:31], v[34:35]
	v_add_u32_e32 v219, v26, v27
	v_lshl_add_u64 v[26:27], v[188:189], 0, s[62:63]
	v_floor_f64_e32 v[22:23], v[22:23]
	v_add_u32_e32 v220, v0, v32
	v_lshl_add_u64 v[28:29], v[26:27], 0, v[70:71]
	v_fma_f64 v[22:23], v[30:31], v[34:35], -v[22:23]
	v_lshl_add_u64 v[28:29], v[28:29], 0, v[72:73]
	v_lshl_add_u64 v[30:31], v[26:27], 0, v[74:75]
	ds_write_b128 v217, v[42:45]
	ds_write_b128 v218, v[46:49]
	ds_write_b128 v219, v[50:53]
	ds_write_b128 v220, v[54:57] offset:25600
	ds_write_b128 v220, v[58:61] offset:34816
	s_lshl_b32 s62, s2, 7
	v_lshl_add_u64 v[30:31], v[30:31], 0, v[76:77]
	global_load_dwordx4 v[156:159], v[28:29], off
	global_load_dwordx4 v[160:163], v[30:31], off
	v_lshl_add_u64 v[26:27], v[26:27], 0, v[78:79]
	v_lshl_add_u64 v[28:29], v[68:69], 0, s[62:63]
	v_lshl_add_u64 v[26:27], v[26:27], 0, v[80:81]
	v_lshl_add_u64 v[28:29], v[28:29], 0, v[0:1]
	v_lshl_add_u64 v[30:31], v[28:29], 0, v[204:205]
	global_load_dwordx4 v[164:167], v[26:27], off
	global_load_dwordx4 v[168:171], v[30:31], off
	v_lshl_add_u64 v[26:27], v[28:29], 0, v[210:211]
	global_load_dwordx4 v[172:175], v[26:27], off
	v_cvt_f32_f64_e32 v23, v[22:23]
	v_sin_f32_e32 v22, v23
	v_cos_f32_e32 v24, v23
	v_sin_f32_e32 v23, v25
	v_cos_f32_e32 v25, v25
	v_mul_f64 v[28:29], v[20:21], v[34:35]
	v_floor_f64_e32 v[28:29], v[28:29]
	v_pk_mul_f32 v[26:27], v[6:7], v[22:23]
	v_fma_f64 v[20:21], v[20:21], v[34:35], -v[28:29]
	v_pk_fma_f32 v[26:27], v[2:3], v[24:25], v[26:27] neg_lo:[0,0,1] neg_hi:[0,0,1]
	v_pk_mul_f32 v[2:3], v[2:3], v[22:23]
	v_mul_f64 v[22:23], v[18:19], v[34:35]
	v_floor_f64_e32 v[22:23], v[22:23]
	v_fma_f64 v[18:19], v[18:19], v[34:35], -v[22:23]
	v_cvt_f32_f64_e32 v19, v[18:19]
	v_cvt_f32_f64_e32 v20, v[20:21]
	v_pk_mul_f32 v[16:17], v[16:17], s[54:55] op_sel_hi:[1,0]
	v_sin_f32_e32 v18, v19
	v_cos_f32_e32 v22, v19
	v_sin_f32_e32 v19, v20
	v_pk_fma_f32 v[2:3], v[6:7], v[24:25], v[2:3]
	v_cos_f32_e32 v23, v20
	v_pk_mul_f32 v[2:3], v[2:3], s[54:55] op_sel_hi:[1,0]
	v_cvt_pk_bf16_f32 v176, v16, v17
	v_or_b32_e32 v16, 0x11000, v0
	v_lshlrev_b32_e32 v0, 5, v221
	v_cvt_pk_bf16_f32 v182, v2, v3
	v_or_b32_e32 v2, v0, v38
	v_mul_lo_u32 v17, v2, s3
	v_mul_u32_u24_e32 v2, 0x90, v38
	v_pk_mul_f32 v[6:7], v[8:9], v[18:19]
	v_lshl_or_b32 v223, v40, 3, v2
	v_or_b32_e32 v2, v39, v38
	v_pk_fma_f32 v[6:7], v[4:5], v[22:23], v[6:7] neg_lo:[0,0,1] neg_hi:[0,0,1]
	v_pk_mul_f32 v[4:5], v[4:5], v[18:19]
	v_sub_u32_e32 v2, v2, v216
	v_pk_mul_f32 v[14:15], v[14:15], s[54:55] op_sel_hi:[1,0]
	v_pk_fma_f32 v[4:5], v[8:9], v[22:23], v[4:5]
	v_add_u32_e32 v224, 0x5f, v0
	v_sub_u32_e32 v0, v2, v0
	s_lshl_b32 s2, s8, 7
	v_pk_mul_f32 v[12:13], v[12:13], s[54:55] op_sel_hi:[1,0]
	v_pk_mul_f32 v[10:11], v[10:11], s[54:55] op_sel_hi:[1,0]
	v_pk_mul_f32 v[26:27], v[26:27], s[54:55] op_sel_hi:[1,0]
	v_pk_mul_f32 v[6:7], v[6:7], s[54:55] op_sel_hi:[1,0]
	v_pk_mul_f32 v[4:5], v[4:5], s[54:55] op_sel_hi:[1,0]
	v_cvt_pk_bf16_f32 v177, v14, v15
	v_lshlrev_b32_e32 v18, 4, v40
	v_add_u32_e32 v19, 0x11000, v223
	v_subrev_u32_e32 v0, s2, v0
	v_mov_b32_e32 v14, v1
	v_mov_b32_e32 v15, v1
	v_cvt_pk_bf16_f32 v135, v64, v65
	v_cvt_pk_bf16_f32 v178, v26, v27
	v_cvt_pk_bf16_f32 v179, v6, v7
	v_cvt_pk_bf16_f32 v180, v12, v13
	v_cvt_pk_bf16_f32 v181, v10, v11
	v_cvt_pk_bf16_f32 v183, v4, v5
	v_add_u32_e32 v225, 0x3f40, v0
	v_mov_b32_e32 v0, v1
	v_mov_b32_e32 v2, v1
	v_mov_b32_e32 v3, v1
	v_mov_b32_e32 v4, v1
	v_mov_b32_e32 v5, v1
	v_mov_b32_e32 v6, v1
	v_mov_b32_e32 v7, v1
	v_mov_b32_e32 v8, v1
	v_mov_b32_e32 v9, v1
	v_mov_b32_e32 v10, v1
	v_mov_b32_e32 v11, v1
	v_mov_b32_e32 v12, v1
	v_mov_b32_e32 v13, v1
	v_add_u32_e32 v226, v16, v32
	v_add_u32_e32 v227, v19, v222
	v_add_u32_e32 v228, v17, v18
	v_mov_b64_e32 v[30:31], v[14:15]
	v_mov_b64_e32 v[46:47], v[14:15]
	v_mov_b64_e32 v[62:63], v[14:15]
	v_mov_b64_e32 v[78:79], v[14:15]
	v_cvt_pk_bf16_f32 v103, v94, v95
	v_mov_b64_e32 v[28:29], v[12:13]
	v_mov_b64_e32 v[26:27], v[10:11]
	v_mov_b64_e32 v[24:25], v[8:9]
	v_mov_b64_e32 v[22:23], v[6:7]
	v_mov_b64_e32 v[20:21], v[4:5]
	v_mov_b64_e32 v[18:19], v[2:3]
	v_mov_b64_e32 v[16:17], v[0:1]
	v_mov_b64_e32 v[44:45], v[12:13]
	v_mov_b64_e32 v[42:43], v[10:11]
	v_mov_b64_e32 v[40:41], v[8:9]
	v_mov_b64_e32 v[38:39], v[6:7]
	v_mov_b64_e32 v[36:37], v[4:5]
	v_mov_b64_e32 v[34:35], v[2:3]
	v_mov_b64_e32 v[32:33], v[0:1]
	v_mov_b64_e32 v[60:61], v[12:13]
	v_mov_b64_e32 v[58:59], v[10:11]
	v_mov_b64_e32 v[56:57], v[8:9]
	v_mov_b64_e32 v[54:55], v[6:7]
	v_mov_b64_e32 v[52:53], v[4:5]
	v_mov_b64_e32 v[50:51], v[2:3]
	v_mov_b64_e32 v[48:49], v[0:1]
	v_mov_b64_e32 v[76:77], v[12:13]
	v_mov_b64_e32 v[74:75], v[10:11]
	v_mov_b64_e32 v[72:73], v[8:9]
	v_mov_b64_e32 v[70:71], v[6:7]
	v_mov_b64_e32 v[68:69], v[4:5]
	v_mov_b64_e32 v[66:67], v[2:3]
	v_mov_b64_e32 v[64:65], v[0:1]
	s_waitcnt lgkmcnt(0)
	s_barrier
	s_branch .LBB0_644
